# scan consumer: loads at step head, one lgkm wait per four steps (8 register sets, prefetch distance 4)
# speedup vs baseline: 1.0144x; 1.0000x over previous
.LBB0_56:
	s_and_b64 s[4:5], s[42:43], exec
	s_mov_b32 s4, 0x1caf0000
	s_cselect_b32 s4, s4, 0x14af0000
	s_add_u32 s4, s30, s4
	s_addc_u32 s5, s31, 0
	s_lshl_b32 s6, s37, 1
	v_lshl_add_u32 v0, s64, 4, v58
	s_add_u32 s4, s4, s6
	s_addc_u32 s5, s5, 0
	v_ashrrev_i32_e32 v1, 31, v0
	s_waitcnt lgkmcnt(0)
	s_barrier
	v_lshl_add_u64 v[0:1], v[0:1], 1, s[4:5]
	s_and_b64 s[4:5], s[42:43], exec
	s_movk_i32 s4, 0x4000
	s_mov_b32 s28, 0
	s_cselect_b32 s85, 0, -1
	s_cselect_b32 s84, s4, 0xffffc000
	s_waitcnt vmcnt(0)
	v_mov_b32_e32 v6, 0
	v_mov_b32_e32 v4, v78
	v_mov_b32_e32 v5, v15
	v_mov_b32_e32 v7, 0
	v_mov_b32_e32 v8, 0
	v_mov_b32_e32 v9, 0
	v_lshlrev_b32_e32 v74, 4, v58
	v_add_u32_e32 v74, 0x22000, v74
	v_mov_b32_e32 v10, v59
	v_mov_b32_e32 v11, v74
	ds_read_b128 v[66:69], v11 offset:0
	ds_read_b128 v[20:23], v10 offset:256
	ds_read_b128 v[28:31], v10 offset:768
	ds_read_b128 v[24:27], v10 offset:512
	ds_read_b128 v[36:39], v10 offset:1280
	ds_read_b128 v[44:47], v10 offset:1792
	ds_read_b128 v[40:43], v10 offset:1536
	ds_read_b128 v[88:91], v10 offset:2304
	ds_read_b128 v[96:99], v10 offset:2816
	ds_read_b128 v[92:95], v10 offset:2560
	ds_read_b128 v[110:113], v10 offset:3328
	ds_read_b128 v[106:109], v10 offset:3072
	ds_read_b128 v[118:121], v10 offset:3840
	ds_read_b128 v[114:117], v10 offset:3584
.Lscan_cons_chunk:
	v_cndmask_b32_e64 v2, v4, v5, s[42:43]
	v_add_lshl_u32 v2, v2, s80, 10
	v_mov_b32_e32 v3, v180
	s_add_i32 s28, s28, 0x10000
	v_lshl_add_u64 v[2:3], v[0:1], 0, v[2:3]
	v_add_u32_e32 v5, 64, v5
	v_subrev_u32_e32 v4, 64, v4
	s_waitcnt lgkmcnt(0)
	ds_read_b128 v[142:145], v10 offset:4352
	ds_read_b128 v[150:153], v10 offset:4864
	ds_read_b128 v[146:149], v10 offset:4608
	v_fma_mix_f32 v12, v6, v20, v180 op_sel_hi:[0,1,0]
	v_fma_mix_f32 v12, v7, v20, v12 op_sel:[0,1,0] op_sel_hi:[0,1,0]
	v_fma_mix_f32 v12, v8, v21, v12 op_sel_hi:[0,1,0]
	v_fma_mix_f32 v12, v9, v21, v12 op_sel:[0,1,0] op_sel_hi:[0,1,0]
	s_nop 1
	v_add_f32_dpp v12, v12, v12 row_ror:1 row_mask:0xf bank_mask:0xf bound_ctrl:1
	s_nop 1
	v_add_f32_dpp v12, v12, v12 row_ror:2 row_mask:0xf bank_mask:0xf bound_ctrl:1
	v_pk_fma_f32 v[48:49], v[28:29], v[66:67], v[6:7] op_sel_hi:[1,0,1]
	v_pk_fma_f32 v[50:51], v[30:31], v[66:67], v[8:9] op_sel_hi:[1,0,1]
	v_add_f32_dpp v12, v12, v12 row_ror:4 row_mask:0xf bank_mask:0xf bound_ctrl:1
	s_nop 1
	v_add_f32_dpp v12, v12, v12 row_ror:8 row_mask:0xf bank_mask:0xf bound_ctrl:1
	v_pk_fma_f32 v[6:7], v[24:25], v[12:13], v[48:49] op_sel_hi:[1,0,1] neg_lo:[1,0,0] neg_hi:[1,0,0]
	v_pk_fma_f32 v[8:9], v[26:27], v[12:13], v[50:51] op_sel_hi:[1,0,1] neg_lo:[1,0,0] neg_hi:[1,0,0]
	ds_read_b128 v[158:161], v10 offset:5376
	ds_read_b128 v[166:169], v10 offset:5888
	ds_read_b128 v[162:165], v10 offset:5632
	ds_read_b128 v[70:73], v11 offset:256
	v_fma_mix_f32 v12, v6, v36, v180 op_sel_hi:[0,1,0]
	v_fma_mix_f32 v12, v7, v36, v12 op_sel:[0,1,0] op_sel_hi:[0,1,0]
	v_fma_mix_f32 v12, v8, v37, v12 op_sel_hi:[0,1,0]
	v_fma_mix_f32 v12, v9, v37, v12 op_sel:[0,1,0] op_sel_hi:[0,1,0]
	v_fma_mix_f32 v52, v6, v22, v180 op_sel_hi:[0,1,0]
	v_fma_mix_f32 v52, v7, v22, v52 op_sel:[0,1,0] op_sel_hi:[0,1,0]
	v_add_f32_dpp v12, v12, v12 row_ror:1 row_mask:0xf bank_mask:0xf bound_ctrl:1
	v_fma_mix_f32 v52, v8, v23, v52 op_sel_hi:[0,1,0]
	v_fma_mix_f32 v52, v9, v23, v52 op_sel:[0,1,0] op_sel_hi:[0,1,0]
	v_add_f32_dpp v12, v12, v12 row_ror:2 row_mask:0xf bank_mask:0xf bound_ctrl:1
	v_pk_fma_f32 v[48:49], v[44:45], v[66:67], v[6:7] op_sel:[0,1,0]
	v_pk_fma_f32 v[50:51], v[46:47], v[66:67], v[8:9] op_sel:[0,1,0]
	v_add_f32_dpp v12, v12, v12 row_ror:4 row_mask:0xf bank_mask:0xf bound_ctrl:1
	s_nop 1
	v_add_f32_dpp v12, v12, v12 row_ror:8 row_mask:0xf bank_mask:0xf bound_ctrl:1
	v_pk_fma_f32 v[6:7], v[40:41], v[12:13], v[48:49] op_sel_hi:[1,0,1] neg_lo:[1,0,0] neg_hi:[1,0,0]
	v_pk_fma_f32 v[8:9], v[42:43], v[12:13], v[50:51] op_sel_hi:[1,0,1] neg_lo:[1,0,0] neg_hi:[1,0,0]
	ds_read_b128 v[188:191], v10 offset:6400
	ds_read_b128 v[196:199], v10 offset:6912
	ds_read_b128 v[192:195], v10 offset:6656
	v_fma_mix_f32 v12, v6, v88, v180 op_sel_hi:[0,1,0]
	v_fma_mix_f32 v12, v7, v88, v12 op_sel:[0,1,0] op_sel_hi:[0,1,0]
	v_fma_mix_f32 v12, v8, v89, v12 op_sel_hi:[0,1,0]
	v_fma_mix_f32 v12, v9, v89, v12 op_sel:[0,1,0] op_sel_hi:[0,1,0]
	v_fma_mix_f32 v53, v6, v38, v180 op_sel_hi:[0,1,0]
	v_fma_mix_f32 v53, v7, v38, v53 op_sel:[0,1,0] op_sel_hi:[0,1,0]
	v_add_f32_dpp v12, v12, v12 row_ror:1 row_mask:0xf bank_mask:0xf bound_ctrl:1
	v_fma_mix_f32 v53, v8, v39, v53 op_sel_hi:[0,1,0]
	v_fma_mix_f32 v53, v9, v39, v53 op_sel:[0,1,0] op_sel_hi:[0,1,0]
	v_add_f32_dpp v12, v12, v12 row_ror:2 row_mask:0xf bank_mask:0xf bound_ctrl:1
	v_pk_fma_f32 v[48:49], v[96:97], v[68:69], v[6:7] op_sel_hi:[1,0,1]
	v_pk_fma_f32 v[50:51], v[98:99], v[68:69], v[8:9] op_sel_hi:[1,0,1]
	v_add_f32_dpp v12, v12, v12 row_ror:4 row_mask:0xf bank_mask:0xf bound_ctrl:1
	s_nop 1
	v_add_f32_dpp v12, v12, v12 row_ror:8 row_mask:0xf bank_mask:0xf bound_ctrl:1
	v_pk_fma_f32 v[6:7], v[92:93], v[12:13], v[48:49] op_sel_hi:[1,0,1] neg_lo:[1,0,0] neg_hi:[1,0,0]
	v_pk_fma_f32 v[8:9], v[94:95], v[12:13], v[50:51] op_sel_hi:[1,0,1] neg_lo:[1,0,0] neg_hi:[1,0,0]
	ds_read_b128 v[204:207], v10 offset:7424
	ds_read_b128 v[200:203], v10 offset:7168
	ds_read_b128 v[212:215], v10 offset:7936
	ds_read_b128 v[208:211], v10 offset:7680
	v_fma_mix_f32 v12, v6, v110, v180 op_sel_hi:[0,1,0]
	v_fma_mix_f32 v12, v7, v110, v12 op_sel:[0,1,0] op_sel_hi:[0,1,0]
	v_fma_mix_f32 v12, v8, v111, v12 op_sel_hi:[0,1,0]
	v_fma_mix_f32 v12, v9, v111, v12 op_sel:[0,1,0] op_sel_hi:[0,1,0]
	v_fma_mix_f32 v54, v6, v90, v180 op_sel_hi:[0,1,0]
	v_fma_mix_f32 v54, v7, v90, v54 op_sel:[0,1,0] op_sel_hi:[0,1,0]
	v_add_f32_dpp v12, v12, v12 row_ror:1 row_mask:0xf bank_mask:0xf bound_ctrl:1
	v_fma_mix_f32 v54, v8, v91, v54 op_sel_hi:[0,1,0]
	v_fma_mix_f32 v54, v9, v91, v54 op_sel:[0,1,0] op_sel_hi:[0,1,0]
	v_add_f32_dpp v12, v12, v12 row_ror:2 row_mask:0xf bank_mask:0xf bound_ctrl:1
	v_pk_fma_f32 v[48:49], v[118:119], v[68:69], v[6:7] op_sel:[0,1,0]
	v_pk_fma_f32 v[50:51], v[120:121], v[68:69], v[8:9] op_sel:[0,1,0]
	v_add_f32_dpp v12, v12, v12 row_ror:4 row_mask:0xf bank_mask:0xf bound_ctrl:1
	s_nop 1
	v_add_f32_dpp v12, v12, v12 row_ror:8 row_mask:0xf bank_mask:0xf bound_ctrl:1
	v_pk_fma_f32 v[6:7], v[114:115], v[12:13], v[48:49] op_sel_hi:[1,0,1] neg_lo:[1,0,0] neg_hi:[1,0,0]
	v_pk_fma_f32 v[8:9], v[116:117], v[12:13], v[50:51] op_sel_hi:[1,0,1] neg_lo:[1,0,0] neg_hi:[1,0,0]
	v_pk_mul_f32 v[6:7], v[6:7], v[106:107]
	v_pk_mul_f32 v[8:9], v[8:9], v[108:109]
	s_waitcnt lgkmcnt(0)
	ds_read_b128 v[20:23], v10 offset:8448
	ds_read_b128 v[28:31], v10 offset:8960
	ds_read_b128 v[24:27], v10 offset:8704
	v_fma_mix_f32 v12, v6, v142, v180 op_sel_hi:[0,1,0]
	v_fma_mix_f32 v12, v7, v142, v12 op_sel:[0,1,0] op_sel_hi:[0,1,0]
	v_fma_mix_f32 v12, v8, v143, v12 op_sel_hi:[0,1,0]
	v_fma_mix_f32 v12, v9, v143, v12 op_sel:[0,1,0] op_sel_hi:[0,1,0]
	v_fma_mix_f32 v55, v6, v112, v180 op_sel_hi:[0,1,0]
	v_fma_mix_f32 v55, v7, v112, v55 op_sel:[0,1,0] op_sel_hi:[0,1,0]
	v_add_f32_dpp v12, v12, v12 row_ror:1 row_mask:0xf bank_mask:0xf bound_ctrl:1
	v_fma_mix_f32 v55, v8, v113, v55 op_sel_hi:[0,1,0]
	v_fma_mix_f32 v55, v9, v113, v55 op_sel:[0,1,0] op_sel_hi:[0,1,0]
	v_add_f32_dpp v12, v12, v12 row_ror:2 row_mask:0xf bank_mask:0xf bound_ctrl:1
	v_pk_fma_f32 v[48:49], v[150:151], v[70:71], v[6:7] op_sel_hi:[1,0,1]
	v_pk_fma_f32 v[50:51], v[152:153], v[70:71], v[8:9] op_sel_hi:[1,0,1]
	v_add_f32_dpp v12, v12, v12 row_ror:4 row_mask:0xf bank_mask:0xf bound_ctrl:1
	s_nop 1
	v_add_f32_dpp v12, v12, v12 row_ror:8 row_mask:0xf bank_mask:0xf bound_ctrl:1
	v_pk_fma_f32 v[6:7], v[146:147], v[12:13], v[48:49] op_sel_hi:[1,0,1] neg_lo:[1,0,0] neg_hi:[1,0,0]
	v_pk_fma_f32 v[8:9], v[148:149], v[12:13], v[50:51] op_sel_hi:[1,0,1] neg_lo:[1,0,0] neg_hi:[1,0,0]
	ds_read_b128 v[36:39], v10 offset:9472
	ds_read_b128 v[44:47], v10 offset:9984
	ds_read_b128 v[40:43], v10 offset:9728
	ds_read_b128 v[66:69], v11 offset:512
	v_fma_mix_f32 v12, v6, v158, v180 op_sel_hi:[0,1,0]
	v_fma_mix_f32 v12, v7, v158, v12 op_sel:[0,1,0] op_sel_hi:[0,1,0]
	v_fma_mix_f32 v12, v8, v159, v12 op_sel_hi:[0,1,0]
	v_fma_mix_f32 v12, v9, v159, v12 op_sel:[0,1,0] op_sel_hi:[0,1,0]
	v_fma_mix_f32 v56, v6, v144, v180 op_sel_hi:[0,1,0]
	v_fma_mix_f32 v56, v7, v144, v56 op_sel:[0,1,0] op_sel_hi:[0,1,0]
	v_add_f32_dpp v12, v12, v12 row_ror:1 row_mask:0xf bank_mask:0xf bound_ctrl:1
	v_fma_mix_f32 v56, v8, v145, v56 op_sel_hi:[0,1,0]
	v_fma_mix_f32 v56, v9, v145, v56 op_sel:[0,1,0] op_sel_hi:[0,1,0]
	v_add_f32_dpp v12, v12, v12 row_ror:2 row_mask:0xf bank_mask:0xf bound_ctrl:1
	v_pk_fma_f32 v[48:49], v[166:167], v[70:71], v[6:7] op_sel:[0,1,0]
	v_pk_fma_f32 v[50:51], v[168:169], v[70:71], v[8:9] op_sel:[0,1,0]
	v_add_f32_dpp v12, v12, v12 row_ror:4 row_mask:0xf bank_mask:0xf bound_ctrl:1
	s_nop 1
	v_add_f32_dpp v12, v12, v12 row_ror:8 row_mask:0xf bank_mask:0xf bound_ctrl:1
	v_pk_fma_f32 v[6:7], v[162:163], v[12:13], v[48:49] op_sel_hi:[1,0,1] neg_lo:[1,0,0] neg_hi:[1,0,0]
	v_pk_fma_f32 v[8:9], v[164:165], v[12:13], v[50:51] op_sel_hi:[1,0,1] neg_lo:[1,0,0] neg_hi:[1,0,0]
	ds_read_b128 v[88:91], v10 offset:10496
	ds_read_b128 v[96:99], v10 offset:11008
	ds_read_b128 v[92:95], v10 offset:10752
	v_fma_mix_f32 v12, v6, v188, v180 op_sel_hi:[0,1,0]
	v_fma_mix_f32 v12, v7, v188, v12 op_sel:[0,1,0] op_sel_hi:[0,1,0]
	v_fma_mix_f32 v12, v8, v189, v12 op_sel_hi:[0,1,0]
	v_fma_mix_f32 v12, v9, v189, v12 op_sel:[0,1,0] op_sel_hi:[0,1,0]
	v_fma_mix_f32 v57, v6, v160, v180 op_sel_hi:[0,1,0]
	v_fma_mix_f32 v57, v7, v160, v57 op_sel:[0,1,0] op_sel_hi:[0,1,0]
	v_add_f32_dpp v12, v12, v12 row_ror:1 row_mask:0xf bank_mask:0xf bound_ctrl:1
	v_fma_mix_f32 v57, v8, v161, v57 op_sel_hi:[0,1,0]
	v_fma_mix_f32 v57, v9, v161, v57 op_sel:[0,1,0] op_sel_hi:[0,1,0]
	v_add_f32_dpp v12, v12, v12 row_ror:2 row_mask:0xf bank_mask:0xf bound_ctrl:1
	v_pk_fma_f32 v[48:49], v[196:197], v[72:73], v[6:7] op_sel_hi:[1,0,1]
	v_pk_fma_f32 v[50:51], v[198:199], v[72:73], v[8:9] op_sel_hi:[1,0,1]
	v_add_f32_dpp v12, v12, v12 row_ror:4 row_mask:0xf bank_mask:0xf bound_ctrl:1
	s_nop 1
	v_add_f32_dpp v12, v12, v12 row_ror:8 row_mask:0xf bank_mask:0xf bound_ctrl:1
	v_pk_fma_f32 v[6:7], v[192:193], v[12:13], v[48:49] op_sel_hi:[1,0,1] neg_lo:[1,0,0] neg_hi:[1,0,0]
	v_pk_fma_f32 v[8:9], v[194:195], v[12:13], v[50:51] op_sel_hi:[1,0,1] neg_lo:[1,0,0] neg_hi:[1,0,0]
	ds_read_b128 v[110:113], v10 offset:11520
	ds_read_b128 v[106:109], v10 offset:11264
	ds_read_b128 v[118:121], v10 offset:12032
	ds_read_b128 v[114:117], v10 offset:11776
	v_fma_mix_f32 v12, v6, v204, v180 op_sel_hi:[0,1,0]
	v_fma_mix_f32 v12, v7, v204, v12 op_sel:[0,1,0] op_sel_hi:[0,1,0]
	v_fma_mix_f32 v12, v8, v205, v12 op_sel_hi:[0,1,0]
	v_fma_mix_f32 v12, v9, v205, v12 op_sel:[0,1,0] op_sel_hi:[0,1,0]
	v_fma_mix_f32 v81, v6, v190, v180 op_sel_hi:[0,1,0]
	v_fma_mix_f32 v81, v7, v190, v81 op_sel:[0,1,0] op_sel_hi:[0,1,0]
	v_add_f32_dpp v12, v12, v12 row_ror:1 row_mask:0xf bank_mask:0xf bound_ctrl:1
	v_fma_mix_f32 v81, v8, v191, v81 op_sel_hi:[0,1,0]
	v_fma_mix_f32 v81, v9, v191, v81 op_sel:[0,1,0] op_sel_hi:[0,1,0]
	v_add_f32_dpp v12, v12, v12 row_ror:2 row_mask:0xf bank_mask:0xf bound_ctrl:1
	v_pk_fma_f32 v[48:49], v[212:213], v[72:73], v[6:7] op_sel:[0,1,0]
	v_pk_fma_f32 v[50:51], v[214:215], v[72:73], v[8:9] op_sel:[0,1,0]
	v_add_f32_dpp v12, v12, v12 row_ror:4 row_mask:0xf bank_mask:0xf bound_ctrl:1
	s_nop 1
	v_add_f32_dpp v12, v12, v12 row_ror:8 row_mask:0xf bank_mask:0xf bound_ctrl:1
	v_pk_fma_f32 v[6:7], v[208:209], v[12:13], v[48:49] op_sel_hi:[1,0,1] neg_lo:[1,0,0] neg_hi:[1,0,0]
	v_pk_fma_f32 v[8:9], v[210:211], v[12:13], v[50:51] op_sel_hi:[1,0,1] neg_lo:[1,0,0] neg_hi:[1,0,0]
	v_pk_mul_f32 v[6:7], v[6:7], v[200:201]
	v_pk_mul_f32 v[8:9], v[8:9], v[202:203]
	s_waitcnt lgkmcnt(0)
	ds_read_b128 v[142:145], v10 offset:12544
	ds_read_b128 v[150:153], v10 offset:13056
	ds_read_b128 v[146:149], v10 offset:12800
	v_fma_mix_f32 v12, v6, v20, v180 op_sel_hi:[0,1,0]
	v_fma_mix_f32 v12, v7, v20, v12 op_sel:[0,1,0] op_sel_hi:[0,1,0]
	v_fma_mix_f32 v12, v8, v21, v12 op_sel_hi:[0,1,0]
	v_fma_mix_f32 v12, v9, v21, v12 op_sel:[0,1,0] op_sel_hi:[0,1,0]
	v_fma_mix_f32 v82, v6, v206, v180 op_sel_hi:[0,1,0]
	v_fma_mix_f32 v82, v7, v206, v82 op_sel:[0,1,0] op_sel_hi:[0,1,0]
	v_add_f32_dpp v12, v12, v12 row_ror:1 row_mask:0xf bank_mask:0xf bound_ctrl:1
	v_fma_mix_f32 v82, v8, v207, v82 op_sel_hi:[0,1,0]
	v_fma_mix_f32 v82, v9, v207, v82 op_sel:[0,1,0] op_sel_hi:[0,1,0]
	v_add_f32_dpp v12, v12, v12 row_ror:2 row_mask:0xf bank_mask:0xf bound_ctrl:1
	v_pk_fma_f32 v[48:49], v[28:29], v[66:67], v[6:7] op_sel_hi:[1,0,1]
	v_pk_fma_f32 v[50:51], v[30:31], v[66:67], v[8:9] op_sel_hi:[1,0,1]
	v_add_f32_dpp v12, v12, v12 row_ror:4 row_mask:0xf bank_mask:0xf bound_ctrl:1
	s_nop 1
	v_add_f32_dpp v12, v12, v12 row_ror:8 row_mask:0xf bank_mask:0xf bound_ctrl:1
	v_pk_fma_f32 v[6:7], v[24:25], v[12:13], v[48:49] op_sel_hi:[1,0,1] neg_lo:[1,0,0] neg_hi:[1,0,0]
	v_pk_fma_f32 v[8:9], v[26:27], v[12:13], v[50:51] op_sel_hi:[1,0,1] neg_lo:[1,0,0] neg_hi:[1,0,0]
	ds_read_b128 v[158:161], v10 offset:13568
	ds_read_b128 v[166:169], v10 offset:14080
	ds_read_b128 v[162:165], v10 offset:13824
	ds_read_b128 v[70:73], v11 offset:768
	v_fma_mix_f32 v12, v6, v36, v180 op_sel_hi:[0,1,0]
	v_fma_mix_f32 v12, v7, v36, v12 op_sel:[0,1,0] op_sel_hi:[0,1,0]
	v_fma_mix_f32 v12, v8, v37, v12 op_sel_hi:[0,1,0]
	v_fma_mix_f32 v12, v9, v37, v12 op_sel:[0,1,0] op_sel_hi:[0,1,0]
	v_fma_mix_f32 v83, v6, v22, v180 op_sel_hi:[0,1,0]
	v_fma_mix_f32 v83, v7, v22, v83 op_sel:[0,1,0] op_sel_hi:[0,1,0]
	v_add_f32_dpp v12, v12, v12 row_ror:1 row_mask:0xf bank_mask:0xf bound_ctrl:1
	v_fma_mix_f32 v83, v8, v23, v83 op_sel_hi:[0,1,0]
	v_fma_mix_f32 v83, v9, v23, v83 op_sel:[0,1,0] op_sel_hi:[0,1,0]
	v_add_f32_dpp v12, v12, v12 row_ror:2 row_mask:0xf bank_mask:0xf bound_ctrl:1
	v_pk_fma_f32 v[48:49], v[44:45], v[66:67], v[6:7] op_sel:[0,1,0]
	v_pk_fma_f32 v[50:51], v[46:47], v[66:67], v[8:9] op_sel:[0,1,0]
	v_add_f32_dpp v12, v12, v12 row_ror:4 row_mask:0xf bank_mask:0xf bound_ctrl:1
	s_nop 1
	v_add_f32_dpp v12, v12, v12 row_ror:8 row_mask:0xf bank_mask:0xf bound_ctrl:1
	v_pk_fma_f32 v[6:7], v[40:41], v[12:13], v[48:49] op_sel_hi:[1,0,1] neg_lo:[1,0,0] neg_hi:[1,0,0]
	v_pk_fma_f32 v[8:9], v[42:43], v[12:13], v[50:51] op_sel_hi:[1,0,1] neg_lo:[1,0,0] neg_hi:[1,0,0]
	ds_read_b128 v[188:191], v10 offset:14592
	ds_read_b128 v[196:199], v10 offset:15104
	ds_read_b128 v[192:195], v10 offset:14848
	v_fma_mix_f32 v12, v6, v88, v180 op_sel_hi:[0,1,0]
	v_fma_mix_f32 v12, v7, v88, v12 op_sel:[0,1,0] op_sel_hi:[0,1,0]
	v_fma_mix_f32 v12, v8, v89, v12 op_sel_hi:[0,1,0]
	v_fma_mix_f32 v12, v9, v89, v12 op_sel:[0,1,0] op_sel_hi:[0,1,0]
	v_fma_mix_f32 v100, v6, v38, v180 op_sel_hi:[0,1,0]
	v_fma_mix_f32 v100, v7, v38, v100 op_sel:[0,1,0] op_sel_hi:[0,1,0]
	v_add_f32_dpp v12, v12, v12 row_ror:1 row_mask:0xf bank_mask:0xf bound_ctrl:1
	v_fma_mix_f32 v100, v8, v39, v100 op_sel_hi:[0,1,0]
	v_fma_mix_f32 v100, v9, v39, v100 op_sel:[0,1,0] op_sel_hi:[0,1,0]
	v_add_f32_dpp v12, v12, v12 row_ror:2 row_mask:0xf bank_mask:0xf bound_ctrl:1
	v_pk_fma_f32 v[48:49], v[96:97], v[68:69], v[6:7] op_sel_hi:[1,0,1]
	v_pk_fma_f32 v[50:51], v[98:99], v[68:69], v[8:9] op_sel_hi:[1,0,1]
	v_add_f32_dpp v12, v12, v12 row_ror:4 row_mask:0xf bank_mask:0xf bound_ctrl:1
	s_nop 1
	v_add_f32_dpp v12, v12, v12 row_ror:8 row_mask:0xf bank_mask:0xf bound_ctrl:1
	v_pk_fma_f32 v[6:7], v[92:93], v[12:13], v[48:49] op_sel_hi:[1,0,1] neg_lo:[1,0,0] neg_hi:[1,0,0]
	v_pk_fma_f32 v[8:9], v[94:95], v[12:13], v[50:51] op_sel_hi:[1,0,1] neg_lo:[1,0,0] neg_hi:[1,0,0]
	ds_read_b128 v[204:207], v10 offset:15616
	ds_read_b128 v[200:203], v10 offset:15360
	ds_read_b128 v[212:215], v10 offset:16128
	ds_read_b128 v[208:211], v10 offset:15872
	v_fma_mix_f32 v12, v6, v110, v180 op_sel_hi:[0,1,0]
	v_fma_mix_f32 v12, v7, v110, v12 op_sel:[0,1,0] op_sel_hi:[0,1,0]
	v_fma_mix_f32 v12, v8, v111, v12 op_sel_hi:[0,1,0]
	v_fma_mix_f32 v12, v9, v111, v12 op_sel:[0,1,0] op_sel_hi:[0,1,0]
	v_fma_mix_f32 v101, v6, v90, v180 op_sel_hi:[0,1,0]
	v_fma_mix_f32 v101, v7, v90, v101 op_sel:[0,1,0] op_sel_hi:[0,1,0]
	v_add_f32_dpp v12, v12, v12 row_ror:1 row_mask:0xf bank_mask:0xf bound_ctrl:1
	v_fma_mix_f32 v101, v8, v91, v101 op_sel_hi:[0,1,0]
	v_fma_mix_f32 v101, v9, v91, v101 op_sel:[0,1,0] op_sel_hi:[0,1,0]
	v_add_f32_dpp v12, v12, v12 row_ror:2 row_mask:0xf bank_mask:0xf bound_ctrl:1
	v_pk_fma_f32 v[48:49], v[118:119], v[68:69], v[6:7] op_sel:[0,1,0]
	v_pk_fma_f32 v[50:51], v[120:121], v[68:69], v[8:9] op_sel:[0,1,0]
	v_add_f32_dpp v12, v12, v12 row_ror:4 row_mask:0xf bank_mask:0xf bound_ctrl:1
	s_nop 1
	v_add_f32_dpp v12, v12, v12 row_ror:8 row_mask:0xf bank_mask:0xf bound_ctrl:1
	v_pk_fma_f32 v[6:7], v[114:115], v[12:13], v[48:49] op_sel_hi:[1,0,1] neg_lo:[1,0,0] neg_hi:[1,0,0]
	v_pk_fma_f32 v[8:9], v[116:117], v[12:13], v[50:51] op_sel_hi:[1,0,1] neg_lo:[1,0,0] neg_hi:[1,0,0]
	v_pk_mul_f32 v[6:7], v[6:7], v[106:107]
	v_pk_mul_f32 v[8:9], v[8:9], v[108:109]
	s_waitcnt lgkmcnt(0)
	ds_read_b128 v[20:23], v10 offset:16640
	ds_read_b128 v[28:31], v10 offset:17152
	ds_read_b128 v[24:27], v10 offset:16896
	v_fma_mix_f32 v12, v6, v142, v180 op_sel_hi:[0,1,0]
	v_fma_mix_f32 v12, v7, v142, v12 op_sel:[0,1,0] op_sel_hi:[0,1,0]
	v_fma_mix_f32 v12, v8, v143, v12 op_sel_hi:[0,1,0]
	v_fma_mix_f32 v12, v9, v143, v12 op_sel:[0,1,0] op_sel_hi:[0,1,0]
	v_fma_mix_f32 v102, v6, v112, v180 op_sel_hi:[0,1,0]
	v_fma_mix_f32 v102, v7, v112, v102 op_sel:[0,1,0] op_sel_hi:[0,1,0]
	v_add_f32_dpp v12, v12, v12 row_ror:1 row_mask:0xf bank_mask:0xf bound_ctrl:1
	v_fma_mix_f32 v102, v8, v113, v102 op_sel_hi:[0,1,0]
	v_fma_mix_f32 v102, v9, v113, v102 op_sel:[0,1,0] op_sel_hi:[0,1,0]
	v_add_f32_dpp v12, v12, v12 row_ror:2 row_mask:0xf bank_mask:0xf bound_ctrl:1
	v_pk_fma_f32 v[48:49], v[150:151], v[70:71], v[6:7] op_sel_hi:[1,0,1]
	v_pk_fma_f32 v[50:51], v[152:153], v[70:71], v[8:9] op_sel_hi:[1,0,1]
	v_add_f32_dpp v12, v12, v12 row_ror:4 row_mask:0xf bank_mask:0xf bound_ctrl:1
	s_nop 1
	v_add_f32_dpp v12, v12, v12 row_ror:8 row_mask:0xf bank_mask:0xf bound_ctrl:1
	v_pk_fma_f32 v[6:7], v[146:147], v[12:13], v[48:49] op_sel_hi:[1,0,1] neg_lo:[1,0,0] neg_hi:[1,0,0]
	v_pk_fma_f32 v[8:9], v[148:149], v[12:13], v[50:51] op_sel_hi:[1,0,1] neg_lo:[1,0,0] neg_hi:[1,0,0]
	ds_read_b128 v[36:39], v10 offset:17664
	ds_read_b128 v[44:47], v10 offset:18176
	ds_read_b128 v[40:43], v10 offset:17920
	ds_read_b128 v[66:69], v11 offset:1024
	v_fma_mix_f32 v12, v6, v158, v180 op_sel_hi:[0,1,0]
	v_fma_mix_f32 v12, v7, v158, v12 op_sel:[0,1,0] op_sel_hi:[0,1,0]
	v_fma_mix_f32 v12, v8, v159, v12 op_sel_hi:[0,1,0]
	v_fma_mix_f32 v12, v9, v159, v12 op_sel:[0,1,0] op_sel_hi:[0,1,0]
	v_fma_mix_f32 v103, v6, v144, v180 op_sel_hi:[0,1,0]
	v_fma_mix_f32 v103, v7, v144, v103 op_sel:[0,1,0] op_sel_hi:[0,1,0]
	v_add_f32_dpp v12, v12, v12 row_ror:1 row_mask:0xf bank_mask:0xf bound_ctrl:1
	v_fma_mix_f32 v103, v8, v145, v103 op_sel_hi:[0,1,0]
	v_fma_mix_f32 v103, v9, v145, v103 op_sel:[0,1,0] op_sel_hi:[0,1,0]
	v_add_f32_dpp v12, v12, v12 row_ror:2 row_mask:0xf bank_mask:0xf bound_ctrl:1
	v_pk_fma_f32 v[48:49], v[166:167], v[70:71], v[6:7] op_sel:[0,1,0]
	v_pk_fma_f32 v[50:51], v[168:169], v[70:71], v[8:9] op_sel:[0,1,0]
	v_add_f32_dpp v12, v12, v12 row_ror:4 row_mask:0xf bank_mask:0xf bound_ctrl:1
	s_nop 1
	v_add_f32_dpp v12, v12, v12 row_ror:8 row_mask:0xf bank_mask:0xf bound_ctrl:1
	v_pk_fma_f32 v[6:7], v[162:163], v[12:13], v[48:49] op_sel_hi:[1,0,1] neg_lo:[1,0,0] neg_hi:[1,0,0]
	v_pk_fma_f32 v[8:9], v[164:165], v[12:13], v[50:51] op_sel_hi:[1,0,1] neg_lo:[1,0,0] neg_hi:[1,0,0]
	ds_read_b128 v[88:91], v10 offset:18688
	ds_read_b128 v[96:99], v10 offset:19200
	ds_read_b128 v[92:95], v10 offset:18944
	v_fma_mix_f32 v12, v6, v188, v180 op_sel_hi:[0,1,0]
	v_fma_mix_f32 v12, v7, v188, v12 op_sel:[0,1,0] op_sel_hi:[0,1,0]
	v_fma_mix_f32 v12, v8, v189, v12 op_sel_hi:[0,1,0]
	v_fma_mix_f32 v12, v9, v189, v12 op_sel:[0,1,0] op_sel_hi:[0,1,0]
	v_fma_mix_f32 v104, v6, v160, v180 op_sel_hi:[0,1,0]
	v_fma_mix_f32 v104, v7, v160, v104 op_sel:[0,1,0] op_sel_hi:[0,1,0]
	v_add_f32_dpp v12, v12, v12 row_ror:1 row_mask:0xf bank_mask:0xf bound_ctrl:1
	v_fma_mix_f32 v104, v8, v161, v104 op_sel_hi:[0,1,0]
	v_fma_mix_f32 v104, v9, v161, v104 op_sel:[0,1,0] op_sel_hi:[0,1,0]
	v_add_f32_dpp v12, v12, v12 row_ror:2 row_mask:0xf bank_mask:0xf bound_ctrl:1
	v_pk_fma_f32 v[48:49], v[196:197], v[72:73], v[6:7] op_sel_hi:[1,0,1]
	v_pk_fma_f32 v[50:51], v[198:199], v[72:73], v[8:9] op_sel_hi:[1,0,1]
	v_add_f32_dpp v12, v12, v12 row_ror:4 row_mask:0xf bank_mask:0xf bound_ctrl:1
	s_nop 1
	v_add_f32_dpp v12, v12, v12 row_ror:8 row_mask:0xf bank_mask:0xf bound_ctrl:1
	v_pk_fma_f32 v[6:7], v[192:193], v[12:13], v[48:49] op_sel_hi:[1,0,1] neg_lo:[1,0,0] neg_hi:[1,0,0]
	v_pk_fma_f32 v[8:9], v[194:195], v[12:13], v[50:51] op_sel_hi:[1,0,1] neg_lo:[1,0,0] neg_hi:[1,0,0]
	ds_read_b128 v[110:113], v10 offset:19712
	ds_read_b128 v[106:109], v10 offset:19456
	ds_read_b128 v[118:121], v10 offset:20224
	ds_read_b128 v[114:117], v10 offset:19968
	v_fma_mix_f32 v12, v6, v204, v180 op_sel_hi:[0,1,0]
	v_fma_mix_f32 v12, v7, v204, v12 op_sel:[0,1,0] op_sel_hi:[0,1,0]
	v_fma_mix_f32 v12, v8, v205, v12 op_sel_hi:[0,1,0]
	v_fma_mix_f32 v12, v9, v205, v12 op_sel:[0,1,0] op_sel_hi:[0,1,0]
	v_fma_mix_f32 v105, v6, v190, v180 op_sel_hi:[0,1,0]
	v_fma_mix_f32 v105, v7, v190, v105 op_sel:[0,1,0] op_sel_hi:[0,1,0]
	v_add_f32_dpp v12, v12, v12 row_ror:1 row_mask:0xf bank_mask:0xf bound_ctrl:1
	v_fma_mix_f32 v105, v8, v191, v105 op_sel_hi:[0,1,0]
	v_fma_mix_f32 v105, v9, v191, v105 op_sel:[0,1,0] op_sel_hi:[0,1,0]
	v_add_f32_dpp v12, v12, v12 row_ror:2 row_mask:0xf bank_mask:0xf bound_ctrl:1
	v_pk_fma_f32 v[48:49], v[212:213], v[72:73], v[6:7] op_sel:[0,1,0]
	v_pk_fma_f32 v[50:51], v[214:215], v[72:73], v[8:9] op_sel:[0,1,0]
	v_add_f32_dpp v12, v12, v12 row_ror:4 row_mask:0xf bank_mask:0xf bound_ctrl:1
	s_nop 1
	v_add_f32_dpp v12, v12, v12 row_ror:8 row_mask:0xf bank_mask:0xf bound_ctrl:1
	v_pk_fma_f32 v[6:7], v[208:209], v[12:13], v[48:49] op_sel_hi:[1,0,1] neg_lo:[1,0,0] neg_hi:[1,0,0]
	v_pk_fma_f32 v[8:9], v[210:211], v[12:13], v[50:51] op_sel_hi:[1,0,1] neg_lo:[1,0,0] neg_hi:[1,0,0]
	v_pk_mul_f32 v[6:7], v[6:7], v[200:201]
	v_pk_mul_f32 v[8:9], v[8:9], v[202:203]
	s_waitcnt lgkmcnt(0)
	ds_read_b128 v[142:145], v10 offset:20736
	ds_read_b128 v[150:153], v10 offset:21248
	ds_read_b128 v[146:149], v10 offset:20992
	v_fma_mix_f32 v12, v6, v20, v180 op_sel_hi:[0,1,0]
	v_fma_mix_f32 v12, v7, v20, v12 op_sel:[0,1,0] op_sel_hi:[0,1,0]
	v_fma_mix_f32 v12, v8, v21, v12 op_sel_hi:[0,1,0]
	v_fma_mix_f32 v12, v9, v21, v12 op_sel:[0,1,0] op_sel_hi:[0,1,0]
	v_fma_mix_f32 v61, v6, v206, v180 op_sel_hi:[0,1,0]
	v_fma_mix_f32 v61, v7, v206, v61 op_sel:[0,1,0] op_sel_hi:[0,1,0]
	v_add_f32_dpp v12, v12, v12 row_ror:1 row_mask:0xf bank_mask:0xf bound_ctrl:1
	v_fma_mix_f32 v61, v8, v207, v61 op_sel_hi:[0,1,0]
	v_fma_mix_f32 v61, v9, v207, v61 op_sel:[0,1,0] op_sel_hi:[0,1,0]
	v_add_f32_dpp v12, v12, v12 row_ror:2 row_mask:0xf bank_mask:0xf bound_ctrl:1
	v_pk_fma_f32 v[48:49], v[28:29], v[66:67], v[6:7] op_sel_hi:[1,0,1]
	v_pk_fma_f32 v[50:51], v[30:31], v[66:67], v[8:9] op_sel_hi:[1,0,1]
	v_add_f32_dpp v12, v12, v12 row_ror:4 row_mask:0xf bank_mask:0xf bound_ctrl:1
	s_nop 1
	v_add_f32_dpp v12, v12, v12 row_ror:8 row_mask:0xf bank_mask:0xf bound_ctrl:1
	v_pk_fma_f32 v[6:7], v[24:25], v[12:13], v[48:49] op_sel_hi:[1,0,1] neg_lo:[1,0,0] neg_hi:[1,0,0]
	v_pk_fma_f32 v[8:9], v[26:27], v[12:13], v[50:51] op_sel_hi:[1,0,1] neg_lo:[1,0,0] neg_hi:[1,0,0]
	ds_read_b128 v[158:161], v10 offset:21760
	ds_read_b128 v[166:169], v10 offset:22272
	ds_read_b128 v[162:165], v10 offset:22016
	ds_read_b128 v[70:73], v11 offset:1280
	v_fma_mix_f32 v12, v6, v36, v180 op_sel_hi:[0,1,0]
	v_fma_mix_f32 v12, v7, v36, v12 op_sel:[0,1,0] op_sel_hi:[0,1,0]
	v_fma_mix_f32 v12, v8, v37, v12 op_sel_hi:[0,1,0]
	v_fma_mix_f32 v12, v9, v37, v12 op_sel:[0,1,0] op_sel_hi:[0,1,0]
	v_fma_mix_f32 v122, v6, v22, v180 op_sel_hi:[0,1,0]
	v_fma_mix_f32 v122, v7, v22, v122 op_sel:[0,1,0] op_sel_hi:[0,1,0]
	v_add_f32_dpp v12, v12, v12 row_ror:1 row_mask:0xf bank_mask:0xf bound_ctrl:1
	v_fma_mix_f32 v122, v8, v23, v122 op_sel_hi:[0,1,0]
	v_fma_mix_f32 v122, v9, v23, v122 op_sel:[0,1,0] op_sel_hi:[0,1,0]
	v_add_f32_dpp v12, v12, v12 row_ror:2 row_mask:0xf bank_mask:0xf bound_ctrl:1
	v_pk_fma_f32 v[48:49], v[44:45], v[66:67], v[6:7] op_sel:[0,1,0]
	v_pk_fma_f32 v[50:51], v[46:47], v[66:67], v[8:9] op_sel:[0,1,0]
	v_add_f32_dpp v12, v12, v12 row_ror:4 row_mask:0xf bank_mask:0xf bound_ctrl:1
	v_add_f32_dpp v83, v83, v83 row_ror:8 row_mask:0xf bank_mask:0xc
	v_add_f32_dpp v83, v52, v52 row_ror:8 row_mask:0xf bank_mask:0x3
	v_add_f32_dpp v100, v100, v100 row_ror:8 row_mask:0xf bank_mask:0xc
	v_add_f32_dpp v12, v12, v12 row_ror:8 row_mask:0xf bank_mask:0xf bound_ctrl:1
	v_pk_fma_f32 v[6:7], v[40:41], v[12:13], v[48:49] op_sel_hi:[1,0,1] neg_lo:[1,0,0] neg_hi:[1,0,0]
	v_pk_fma_f32 v[8:9], v[42:43], v[12:13], v[50:51] op_sel_hi:[1,0,1] neg_lo:[1,0,0] neg_hi:[1,0,0]
	ds_read_b128 v[188:191], v10 offset:22784
	ds_read_b128 v[196:199], v10 offset:23296
	ds_read_b128 v[192:195], v10 offset:23040
	v_fma_mix_f32 v12, v6, v88, v180 op_sel_hi:[0,1,0]
	v_fma_mix_f32 v12, v7, v88, v12 op_sel:[0,1,0] op_sel_hi:[0,1,0]
	v_fma_mix_f32 v12, v8, v89, v12 op_sel_hi:[0,1,0]
	v_fma_mix_f32 v12, v9, v89, v12 op_sel:[0,1,0] op_sel_hi:[0,1,0]
	v_fma_mix_f32 v123, v6, v38, v180 op_sel_hi:[0,1,0]
	v_fma_mix_f32 v123, v7, v38, v123 op_sel:[0,1,0] op_sel_hi:[0,1,0]
	v_add_f32_dpp v12, v12, v12 row_ror:1 row_mask:0xf bank_mask:0xf bound_ctrl:1
	v_fma_mix_f32 v123, v8, v39, v123 op_sel_hi:[0,1,0]
	v_fma_mix_f32 v123, v9, v39, v123 op_sel:[0,1,0] op_sel_hi:[0,1,0]
	v_add_f32_dpp v12, v12, v12 row_ror:2 row_mask:0xf bank_mask:0xf bound_ctrl:1
	v_pk_fma_f32 v[48:49], v[96:97], v[68:69], v[6:7] op_sel_hi:[1,0,1]
	v_pk_fma_f32 v[50:51], v[98:99], v[68:69], v[8:9] op_sel_hi:[1,0,1]
	v_add_f32_dpp v12, v12, v12 row_ror:4 row_mask:0xf bank_mask:0xf bound_ctrl:1
	v_add_f32_dpp v100, v53, v53 row_ror:8 row_mask:0xf bank_mask:0x3
	v_add_f32_dpp v101, v101, v101 row_ror:8 row_mask:0xf bank_mask:0xc
	v_add_f32_dpp v101, v54, v54 row_ror:8 row_mask:0xf bank_mask:0x3
	v_add_f32_dpp v12, v12, v12 row_ror:8 row_mask:0xf bank_mask:0xf bound_ctrl:1
	v_pk_fma_f32 v[6:7], v[92:93], v[12:13], v[48:49] op_sel_hi:[1,0,1] neg_lo:[1,0,0] neg_hi:[1,0,0]
	v_pk_fma_f32 v[8:9], v[94:95], v[12:13], v[50:51] op_sel_hi:[1,0,1] neg_lo:[1,0,0] neg_hi:[1,0,0]
	ds_read_b128 v[204:207], v10 offset:23808
	ds_read_b128 v[200:203], v10 offset:23552
	ds_read_b128 v[212:215], v10 offset:24320
	ds_read_b128 v[208:211], v10 offset:24064
	v_fma_mix_f32 v12, v6, v110, v180 op_sel_hi:[0,1,0]
	v_fma_mix_f32 v12, v7, v110, v12 op_sel:[0,1,0] op_sel_hi:[0,1,0]
	v_fma_mix_f32 v12, v8, v111, v12 op_sel_hi:[0,1,0]
	v_fma_mix_f32 v12, v9, v111, v12 op_sel:[0,1,0] op_sel_hi:[0,1,0]
	v_fma_mix_f32 v124, v6, v90, v180 op_sel_hi:[0,1,0]
	v_fma_mix_f32 v124, v7, v90, v124 op_sel:[0,1,0] op_sel_hi:[0,1,0]
	v_add_f32_dpp v12, v12, v12 row_ror:1 row_mask:0xf bank_mask:0xf bound_ctrl:1
	v_fma_mix_f32 v124, v8, v91, v124 op_sel_hi:[0,1,0]
	v_fma_mix_f32 v124, v9, v91, v124 op_sel:[0,1,0] op_sel_hi:[0,1,0]
	v_add_f32_dpp v12, v12, v12 row_ror:2 row_mask:0xf bank_mask:0xf bound_ctrl:1
	v_pk_fma_f32 v[48:49], v[118:119], v[68:69], v[6:7] op_sel:[0,1,0]
	v_pk_fma_f32 v[50:51], v[120:121], v[68:69], v[8:9] op_sel:[0,1,0]
	v_add_f32_dpp v12, v12, v12 row_ror:4 row_mask:0xf bank_mask:0xf bound_ctrl:1
	v_add_f32_dpp v102, v102, v102 row_ror:8 row_mask:0xf bank_mask:0xc
	v_add_f32_dpp v102, v55, v55 row_ror:8 row_mask:0xf bank_mask:0x3
	v_add_f32_dpp v103, v103, v103 row_ror:8 row_mask:0xf bank_mask:0xc
	v_add_f32_dpp v12, v12, v12 row_ror:8 row_mask:0xf bank_mask:0xf bound_ctrl:1
	v_pk_fma_f32 v[6:7], v[114:115], v[12:13], v[48:49] op_sel_hi:[1,0,1] neg_lo:[1,0,0] neg_hi:[1,0,0]
	v_pk_fma_f32 v[8:9], v[116:117], v[12:13], v[50:51] op_sel_hi:[1,0,1] neg_lo:[1,0,0] neg_hi:[1,0,0]
	v_pk_mul_f32 v[6:7], v[6:7], v[106:107]
	v_pk_mul_f32 v[8:9], v[8:9], v[108:109]
	s_waitcnt lgkmcnt(0)
	ds_read_b128 v[20:23], v10 offset:24832
	ds_read_b128 v[28:31], v10 offset:25344
	ds_read_b128 v[24:27], v10 offset:25088
	v_fma_mix_f32 v12, v6, v142, v180 op_sel_hi:[0,1,0]
	v_fma_mix_f32 v12, v7, v142, v12 op_sel:[0,1,0] op_sel_hi:[0,1,0]
	v_fma_mix_f32 v12, v8, v143, v12 op_sel_hi:[0,1,0]
	v_fma_mix_f32 v12, v9, v143, v12 op_sel:[0,1,0] op_sel_hi:[0,1,0]
	v_fma_mix_f32 v125, v6, v112, v180 op_sel_hi:[0,1,0]
	v_fma_mix_f32 v125, v7, v112, v125 op_sel:[0,1,0] op_sel_hi:[0,1,0]
	v_add_f32_dpp v12, v12, v12 row_ror:1 row_mask:0xf bank_mask:0xf bound_ctrl:1
	v_fma_mix_f32 v125, v8, v113, v125 op_sel_hi:[0,1,0]
	v_fma_mix_f32 v125, v9, v113, v125 op_sel:[0,1,0] op_sel_hi:[0,1,0]
	v_add_f32_dpp v12, v12, v12 row_ror:2 row_mask:0xf bank_mask:0xf bound_ctrl:1
	v_pk_fma_f32 v[48:49], v[150:151], v[70:71], v[6:7] op_sel_hi:[1,0,1]
	v_pk_fma_f32 v[50:51], v[152:153], v[70:71], v[8:9] op_sel_hi:[1,0,1]
	v_add_f32_dpp v12, v12, v12 row_ror:4 row_mask:0xf bank_mask:0xf bound_ctrl:1
	v_add_f32_dpp v103, v56, v56 row_ror:8 row_mask:0xf bank_mask:0x3
	v_add_f32_dpp v104, v104, v104 row_ror:8 row_mask:0xf bank_mask:0xc
	v_add_f32_dpp v104, v57, v57 row_ror:8 row_mask:0xf bank_mask:0x3
	v_add_f32_dpp v12, v12, v12 row_ror:8 row_mask:0xf bank_mask:0xf bound_ctrl:1
	v_pk_fma_f32 v[6:7], v[146:147], v[12:13], v[48:49] op_sel_hi:[1,0,1] neg_lo:[1,0,0] neg_hi:[1,0,0]
	v_pk_fma_f32 v[8:9], v[148:149], v[12:13], v[50:51] op_sel_hi:[1,0,1] neg_lo:[1,0,0] neg_hi:[1,0,0]
	ds_read_b128 v[36:39], v10 offset:25856
	ds_read_b128 v[44:47], v10 offset:26368
	ds_read_b128 v[40:43], v10 offset:26112
	ds_read_b128 v[66:69], v11 offset:1536
	v_fma_mix_f32 v12, v6, v158, v180 op_sel_hi:[0,1,0]
	v_fma_mix_f32 v12, v7, v158, v12 op_sel:[0,1,0] op_sel_hi:[0,1,0]
	v_fma_mix_f32 v12, v8, v159, v12 op_sel_hi:[0,1,0]
	v_fma_mix_f32 v12, v9, v159, v12 op_sel:[0,1,0] op_sel_hi:[0,1,0]
	v_fma_mix_f32 v126, v6, v144, v180 op_sel_hi:[0,1,0]
	v_fma_mix_f32 v126, v7, v144, v126 op_sel:[0,1,0] op_sel_hi:[0,1,0]
	v_add_f32_dpp v12, v12, v12 row_ror:1 row_mask:0xf bank_mask:0xf bound_ctrl:1
	v_fma_mix_f32 v126, v8, v145, v126 op_sel_hi:[0,1,0]
	v_fma_mix_f32 v126, v9, v145, v126 op_sel:[0,1,0] op_sel_hi:[0,1,0]
	v_add_f32_dpp v12, v12, v12 row_ror:2 row_mask:0xf bank_mask:0xf bound_ctrl:1
	v_pk_fma_f32 v[48:49], v[166:167], v[70:71], v[6:7] op_sel:[0,1,0]
	v_pk_fma_f32 v[50:51], v[168:169], v[70:71], v[8:9] op_sel:[0,1,0]
	v_add_f32_dpp v12, v12, v12 row_ror:4 row_mask:0xf bank_mask:0xf bound_ctrl:1
	v_add_f32_dpp v105, v105, v105 row_ror:8 row_mask:0xf bank_mask:0xc
	v_add_f32_dpp v105, v81, v81 row_ror:8 row_mask:0xf bank_mask:0x3
	v_add_f32_dpp v12, v12, v12 row_ror:8 row_mask:0xf bank_mask:0xf bound_ctrl:1
	v_pk_fma_f32 v[6:7], v[162:163], v[12:13], v[48:49] op_sel_hi:[1,0,1] neg_lo:[1,0,0] neg_hi:[1,0,0]
	v_pk_fma_f32 v[8:9], v[164:165], v[12:13], v[50:51] op_sel_hi:[1,0,1] neg_lo:[1,0,0] neg_hi:[1,0,0]
	ds_read_b128 v[88:91], v10 offset:26880
	ds_read_b128 v[96:99], v10 offset:27392
	ds_read_b128 v[92:95], v10 offset:27136
	v_fma_mix_f32 v12, v6, v188, v180 op_sel_hi:[0,1,0]
	v_fma_mix_f32 v12, v7, v188, v12 op_sel:[0,1,0] op_sel_hi:[0,1,0]
	v_fma_mix_f32 v12, v8, v189, v12 op_sel_hi:[0,1,0]
	v_fma_mix_f32 v12, v9, v189, v12 op_sel:[0,1,0] op_sel_hi:[0,1,0]
	v_fma_mix_f32 v127, v6, v160, v180 op_sel_hi:[0,1,0]
	v_fma_mix_f32 v127, v7, v160, v127 op_sel:[0,1,0] op_sel_hi:[0,1,0]
	v_add_f32_dpp v12, v12, v12 row_ror:1 row_mask:0xf bank_mask:0xf bound_ctrl:1
	v_fma_mix_f32 v127, v8, v161, v127 op_sel_hi:[0,1,0]
	v_fma_mix_f32 v127, v9, v161, v127 op_sel:[0,1,0] op_sel_hi:[0,1,0]
	v_add_f32_dpp v12, v12, v12 row_ror:2 row_mask:0xf bank_mask:0xf bound_ctrl:1
	v_pk_fma_f32 v[48:49], v[196:197], v[72:73], v[6:7] op_sel_hi:[1,0,1]
	v_pk_fma_f32 v[50:51], v[198:199], v[72:73], v[8:9] op_sel_hi:[1,0,1]
	v_add_f32_dpp v12, v12, v12 row_ror:4 row_mask:0xf bank_mask:0xf bound_ctrl:1
	v_add_f32_dpp v61, v61, v61 row_ror:8 row_mask:0xf bank_mask:0xc
	v_add_f32_dpp v61, v82, v82 row_ror:8 row_mask:0xf bank_mask:0x3
	v_add_f32_dpp v12, v12, v12 row_ror:8 row_mask:0xf bank_mask:0xf bound_ctrl:1
	v_pk_fma_f32 v[6:7], v[192:193], v[12:13], v[48:49] op_sel_hi:[1,0,1] neg_lo:[1,0,0] neg_hi:[1,0,0]
	v_pk_fma_f32 v[8:9], v[194:195], v[12:13], v[50:51] op_sel_hi:[1,0,1] neg_lo:[1,0,0] neg_hi:[1,0,0]
	ds_read_b128 v[110:113], v10 offset:27904
	ds_read_b128 v[106:109], v10 offset:27648
	ds_read_b128 v[118:121], v10 offset:28416
	ds_read_b128 v[114:117], v10 offset:28160
	v_fma_mix_f32 v12, v6, v204, v180 op_sel_hi:[0,1,0]
	v_fma_mix_f32 v12, v7, v204, v12 op_sel:[0,1,0] op_sel_hi:[0,1,0]
	v_fma_mix_f32 v12, v8, v205, v12 op_sel_hi:[0,1,0]
	v_fma_mix_f32 v12, v9, v205, v12 op_sel:[0,1,0] op_sel_hi:[0,1,0]
	v_fma_mix_f32 v128, v6, v190, v180 op_sel_hi:[0,1,0]
	v_fma_mix_f32 v128, v7, v190, v128 op_sel:[0,1,0] op_sel_hi:[0,1,0]
	v_add_f32_dpp v12, v12, v12 row_ror:1 row_mask:0xf bank_mask:0xf bound_ctrl:1
	v_fma_mix_f32 v128, v8, v191, v128 op_sel_hi:[0,1,0]
	v_fma_mix_f32 v128, v9, v191, v128 op_sel:[0,1,0] op_sel_hi:[0,1,0]
	v_add_f32_dpp v12, v12, v12 row_ror:2 row_mask:0xf bank_mask:0xf bound_ctrl:1
	v_pk_fma_f32 v[48:49], v[212:213], v[72:73], v[6:7] op_sel:[0,1,0]
	v_pk_fma_f32 v[50:51], v[214:215], v[72:73], v[8:9] op_sel:[0,1,0]
	v_add_f32_dpp v12, v12, v12 row_ror:4 row_mask:0xf bank_mask:0xf bound_ctrl:1
	v_add_f32_dpp v103, v103, v103 row_ror:4 row_mask:0xf bank_mask:0xa
	v_add_f32_dpp v103, v83, v83 row_ror:12 row_mask:0xf bank_mask:0x5
	v_add_f32_dpp v104, v104, v104 row_ror:4 row_mask:0xf bank_mask:0xa
	v_add_f32_dpp v12, v12, v12 row_ror:8 row_mask:0xf bank_mask:0xf bound_ctrl:1
	v_pk_fma_f32 v[6:7], v[208:209], v[12:13], v[48:49] op_sel_hi:[1,0,1] neg_lo:[1,0,0] neg_hi:[1,0,0]
	v_pk_fma_f32 v[8:9], v[210:211], v[12:13], v[50:51] op_sel_hi:[1,0,1] neg_lo:[1,0,0] neg_hi:[1,0,0]
	v_pk_mul_f32 v[6:7], v[6:7], v[200:201]
	v_pk_mul_f32 v[8:9], v[8:9], v[202:203]
	s_waitcnt lgkmcnt(0)
	ds_read_b128 v[142:145], v10 offset:28928
	ds_read_b128 v[150:153], v10 offset:29440
	ds_read_b128 v[146:149], v10 offset:29184
	v_fma_mix_f32 v12, v6, v20, v180 op_sel_hi:[0,1,0]
	v_fma_mix_f32 v12, v7, v20, v12 op_sel:[0,1,0] op_sel_hi:[0,1,0]
	v_fma_mix_f32 v12, v8, v21, v12 op_sel_hi:[0,1,0]
	v_fma_mix_f32 v12, v9, v21, v12 op_sel:[0,1,0] op_sel_hi:[0,1,0]
	v_fma_mix_f32 v129, v6, v206, v180 op_sel_hi:[0,1,0]
	v_fma_mix_f32 v129, v7, v206, v129 op_sel:[0,1,0] op_sel_hi:[0,1,0]
	v_add_f32_dpp v12, v12, v12 row_ror:1 row_mask:0xf bank_mask:0xf bound_ctrl:1
	v_fma_mix_f32 v129, v8, v207, v129 op_sel_hi:[0,1,0]
	v_fma_mix_f32 v129, v9, v207, v129 op_sel:[0,1,0] op_sel_hi:[0,1,0]
	v_add_f32_dpp v12, v12, v12 row_ror:2 row_mask:0xf bank_mask:0xf bound_ctrl:1
	v_pk_fma_f32 v[48:49], v[28:29], v[66:67], v[6:7] op_sel_hi:[1,0,1]
	v_pk_fma_f32 v[50:51], v[30:31], v[66:67], v[8:9] op_sel_hi:[1,0,1]
	v_add_f32_dpp v12, v12, v12 row_ror:4 row_mask:0xf bank_mask:0xf bound_ctrl:1
	v_add_f32_dpp v104, v100, v100 row_ror:12 row_mask:0xf bank_mask:0x5
	v_add_f32_dpp v105, v105, v105 row_ror:4 row_mask:0xf bank_mask:0xa
	v_add_f32_dpp v105, v101, v101 row_ror:12 row_mask:0xf bank_mask:0x5
	v_add_f32_dpp v12, v12, v12 row_ror:8 row_mask:0xf bank_mask:0xf bound_ctrl:1
	v_pk_fma_f32 v[6:7], v[24:25], v[12:13], v[48:49] op_sel_hi:[1,0,1] neg_lo:[1,0,0] neg_hi:[1,0,0]
	v_pk_fma_f32 v[8:9], v[26:27], v[12:13], v[50:51] op_sel_hi:[1,0,1] neg_lo:[1,0,0] neg_hi:[1,0,0]
	ds_read_b128 v[158:161], v10 offset:29952
	ds_read_b128 v[166:169], v10 offset:30464
	ds_read_b128 v[162:165], v10 offset:30208
	ds_read_b128 v[70:73], v11 offset:1792
	v_fma_mix_f32 v12, v6, v36, v180 op_sel_hi:[0,1,0]
	v_fma_mix_f32 v12, v7, v36, v12 op_sel:[0,1,0] op_sel_hi:[0,1,0]
	v_fma_mix_f32 v12, v8, v37, v12 op_sel_hi:[0,1,0]
	v_fma_mix_f32 v12, v9, v37, v12 op_sel:[0,1,0] op_sel_hi:[0,1,0]
	v_fma_mix_f32 v130, v6, v22, v180 op_sel_hi:[0,1,0]
	v_fma_mix_f32 v130, v7, v22, v130 op_sel:[0,1,0] op_sel_hi:[0,1,0]
	v_add_f32_dpp v12, v12, v12 row_ror:1 row_mask:0xf bank_mask:0xf bound_ctrl:1
	v_fma_mix_f32 v130, v8, v23, v130 op_sel_hi:[0,1,0]
	v_fma_mix_f32 v130, v9, v23, v130 op_sel:[0,1,0] op_sel_hi:[0,1,0]
	v_add_f32_dpp v12, v12, v12 row_ror:2 row_mask:0xf bank_mask:0xf bound_ctrl:1
	v_pk_fma_f32 v[48:49], v[44:45], v[66:67], v[6:7] op_sel:[0,1,0]
	v_pk_fma_f32 v[50:51], v[46:47], v[66:67], v[8:9] op_sel:[0,1,0]
	v_add_f32_dpp v12, v12, v12 row_ror:4 row_mask:0xf bank_mask:0xf bound_ctrl:1
	v_add_f32_dpp v61, v61, v61 row_ror:4 row_mask:0xf bank_mask:0xa
	v_add_f32_dpp v61, v102, v102 row_ror:12 row_mask:0xf bank_mask:0x5
	v_add_f32_dpp v12, v12, v12 row_ror:8 row_mask:0xf bank_mask:0xf bound_ctrl:1
	v_pk_fma_f32 v[6:7], v[40:41], v[12:13], v[48:49] op_sel_hi:[1,0,1] neg_lo:[1,0,0] neg_hi:[1,0,0]
	v_pk_fma_f32 v[8:9], v[42:43], v[12:13], v[50:51] op_sel_hi:[1,0,1] neg_lo:[1,0,0] neg_hi:[1,0,0]
	ds_read_b128 v[188:191], v10 offset:30976
	ds_read_b128 v[196:199], v10 offset:31488
	ds_read_b128 v[192:195], v10 offset:31232
	v_fma_mix_f32 v12, v6, v88, v180 op_sel_hi:[0,1,0]
	v_fma_mix_f32 v12, v7, v88, v12 op_sel:[0,1,0] op_sel_hi:[0,1,0]
	v_fma_mix_f32 v12, v8, v89, v12 op_sel_hi:[0,1,0]
	v_fma_mix_f32 v12, v9, v89, v12 op_sel:[0,1,0] op_sel_hi:[0,1,0]
	v_fma_mix_f32 v131, v6, v38, v180 op_sel_hi:[0,1,0]
	v_fma_mix_f32 v131, v7, v38, v131 op_sel:[0,1,0] op_sel_hi:[0,1,0]
	v_add_f32_dpp v12, v12, v12 row_ror:1 row_mask:0xf bank_mask:0xf bound_ctrl:1
	v_fma_mix_f32 v131, v8, v39, v131 op_sel_hi:[0,1,0]
	v_fma_mix_f32 v131, v9, v39, v131 op_sel:[0,1,0] op_sel_hi:[0,1,0]
	v_add_f32_dpp v12, v12, v12 row_ror:2 row_mask:0xf bank_mask:0xf bound_ctrl:1
	v_pk_fma_f32 v[48:49], v[96:97], v[68:69], v[6:7] op_sel_hi:[1,0,1]
	v_pk_fma_f32 v[50:51], v[98:99], v[68:69], v[8:9] op_sel_hi:[1,0,1]
	v_add_f32_dpp v12, v12, v12 row_ror:4 row_mask:0xf bank_mask:0xf bound_ctrl:1
	v_cndmask_b32_e64 v62, v105, v103, s[38:39]
	v_cndmask_b32_e64 v63, v103, v105, s[38:39]
	v_add_f32_dpp v12, v12, v12 row_ror:8 row_mask:0xf bank_mask:0xf bound_ctrl:1
	v_pk_fma_f32 v[6:7], v[92:93], v[12:13], v[48:49] op_sel_hi:[1,0,1] neg_lo:[1,0,0] neg_hi:[1,0,0]
	v_pk_fma_f32 v[8:9], v[94:95], v[12:13], v[50:51] op_sel_hi:[1,0,1] neg_lo:[1,0,0] neg_hi:[1,0,0]
	ds_read_b128 v[204:207], v10 offset:32000
	ds_read_b128 v[200:203], v10 offset:31744
	ds_read_b128 v[212:215], v10 offset:32512
	ds_read_b128 v[208:211], v10 offset:32256
	v_fma_mix_f32 v12, v6, v110, v180 op_sel_hi:[0,1,0]
	v_fma_mix_f32 v12, v7, v110, v12 op_sel:[0,1,0] op_sel_hi:[0,1,0]
	v_fma_mix_f32 v12, v8, v111, v12 op_sel_hi:[0,1,0]
	v_fma_mix_f32 v12, v9, v111, v12 op_sel:[0,1,0] op_sel_hi:[0,1,0]
	v_fma_mix_f32 v132, v6, v90, v180 op_sel_hi:[0,1,0]
	v_fma_mix_f32 v132, v7, v90, v132 op_sel:[0,1,0] op_sel_hi:[0,1,0]
	v_add_f32_dpp v12, v12, v12 row_ror:1 row_mask:0xf bank_mask:0xf bound_ctrl:1
	v_fma_mix_f32 v132, v8, v91, v132 op_sel_hi:[0,1,0]
	v_fma_mix_f32 v132, v9, v91, v132 op_sel:[0,1,0] op_sel_hi:[0,1,0]
	v_add_f32_dpp v12, v12, v12 row_ror:2 row_mask:0xf bank_mask:0xf bound_ctrl:1
	v_pk_fma_f32 v[48:49], v[118:119], v[68:69], v[6:7] op_sel:[0,1,0]
	v_pk_fma_f32 v[50:51], v[120:121], v[68:69], v[8:9] op_sel:[0,1,0]
	v_add_f32_dpp v12, v12, v12 row_ror:4 row_mask:0xf bank_mask:0xf bound_ctrl:1
	v_cndmask_b32_e64 v64, v61, v104, s[38:39]
	v_cndmask_b32_e64 v65, v104, v61, s[38:39]
	v_add_f32_dpp v12, v12, v12 row_ror:8 row_mask:0xf bank_mask:0xf bound_ctrl:1
	v_pk_fma_f32 v[6:7], v[114:115], v[12:13], v[48:49] op_sel_hi:[1,0,1] neg_lo:[1,0,0] neg_hi:[1,0,0]
	v_pk_fma_f32 v[8:9], v[116:117], v[12:13], v[50:51] op_sel_hi:[1,0,1] neg_lo:[1,0,0] neg_hi:[1,0,0]
	v_pk_mul_f32 v[6:7], v[6:7], v[106:107]
	v_pk_mul_f32 v[8:9], v[8:9], v[108:109]
	s_waitcnt lgkmcnt(0)
	ds_read_b128 v[20:23], v10 offset:33024
	ds_read_b128 v[28:31], v10 offset:33536
	ds_read_b128 v[24:27], v10 offset:33280
	v_fma_mix_f32 v12, v6, v142, v180 op_sel_hi:[0,1,0]
	v_fma_mix_f32 v12, v7, v142, v12 op_sel:[0,1,0] op_sel_hi:[0,1,0]
	v_fma_mix_f32 v12, v8, v143, v12 op_sel_hi:[0,1,0]
	v_fma_mix_f32 v12, v9, v143, v12 op_sel:[0,1,0] op_sel_hi:[0,1,0]
	v_fma_mix_f32 v133, v6, v112, v180 op_sel_hi:[0,1,0]
	v_fma_mix_f32 v133, v7, v112, v133 op_sel:[0,1,0] op_sel_hi:[0,1,0]
	v_add_f32_dpp v12, v12, v12 row_ror:1 row_mask:0xf bank_mask:0xf bound_ctrl:1
	v_fma_mix_f32 v133, v8, v113, v133 op_sel_hi:[0,1,0]
	v_fma_mix_f32 v133, v9, v113, v133 op_sel:[0,1,0] op_sel_hi:[0,1,0]
	v_add_f32_dpp v12, v12, v12 row_ror:2 row_mask:0xf bank_mask:0xf bound_ctrl:1
	v_pk_fma_f32 v[48:49], v[150:151], v[70:71], v[6:7] op_sel_hi:[1,0,1]
	v_pk_fma_f32 v[50:51], v[152:153], v[70:71], v[8:9] op_sel_hi:[1,0,1]
	v_add_f32_dpp v12, v12, v12 row_ror:4 row_mask:0xf bank_mask:0xf bound_ctrl:1
	v_add_f32_dpp v62, v63, v62 quad_perm:[2,3,0,1] row_mask:0xf bank_mask:0xf bound_ctrl:1
	v_add_f32_dpp v63, v65, v64 quad_perm:[2,3,0,1] row_mask:0xf bank_mask:0xf bound_ctrl:1
	v_add_f32_dpp v12, v12, v12 row_ror:8 row_mask:0xf bank_mask:0xf bound_ctrl:1
	v_pk_fma_f32 v[6:7], v[146:147], v[12:13], v[48:49] op_sel_hi:[1,0,1] neg_lo:[1,0,0] neg_hi:[1,0,0]
	v_pk_fma_f32 v[8:9], v[148:149], v[12:13], v[50:51] op_sel_hi:[1,0,1] neg_lo:[1,0,0] neg_hi:[1,0,0]
	ds_read_b128 v[36:39], v10 offset:34048
	ds_read_b128 v[44:47], v10 offset:34560
	ds_read_b128 v[40:43], v10 offset:34304
	ds_read_b128 v[66:69], v11 offset:2048
	v_fma_mix_f32 v12, v6, v158, v180 op_sel_hi:[0,1,0]
	v_fma_mix_f32 v12, v7, v158, v12 op_sel:[0,1,0] op_sel_hi:[0,1,0]
	v_fma_mix_f32 v12, v8, v159, v12 op_sel_hi:[0,1,0]
	v_fma_mix_f32 v12, v9, v159, v12 op_sel:[0,1,0] op_sel_hi:[0,1,0]
	v_fma_mix_f32 v134, v6, v144, v180 op_sel_hi:[0,1,0]
	v_fma_mix_f32 v134, v7, v144, v134 op_sel:[0,1,0] op_sel_hi:[0,1,0]
	v_add_f32_dpp v12, v12, v12 row_ror:1 row_mask:0xf bank_mask:0xf bound_ctrl:1
	v_fma_mix_f32 v134, v8, v145, v134 op_sel_hi:[0,1,0]
	v_fma_mix_f32 v134, v9, v145, v134 op_sel:[0,1,0] op_sel_hi:[0,1,0]
	v_add_f32_dpp v12, v12, v12 row_ror:2 row_mask:0xf bank_mask:0xf bound_ctrl:1
	v_pk_fma_f32 v[48:49], v[166:167], v[70:71], v[6:7] op_sel:[0,1,0]
	v_pk_fma_f32 v[50:51], v[168:169], v[70:71], v[8:9] op_sel:[0,1,0]
	v_add_f32_dpp v12, v12, v12 row_ror:4 row_mask:0xf bank_mask:0xf bound_ctrl:1
	v_cndmask_b32_e64 v65, v63, v62, s[40:41]
	v_cndmask_b32_e64 v62, v62, v63, s[40:41]
	v_add_f32_dpp v12, v12, v12 row_ror:8 row_mask:0xf bank_mask:0xf bound_ctrl:1
	v_pk_fma_f32 v[6:7], v[162:163], v[12:13], v[48:49] op_sel_hi:[1,0,1] neg_lo:[1,0,0] neg_hi:[1,0,0]
	v_pk_fma_f32 v[8:9], v[164:165], v[12:13], v[50:51] op_sel_hi:[1,0,1] neg_lo:[1,0,0] neg_hi:[1,0,0]
	ds_read_b128 v[88:91], v10 offset:35072
	ds_read_b128 v[96:99], v10 offset:35584
	ds_read_b128 v[92:95], v10 offset:35328
	v_fma_mix_f32 v12, v6, v188, v180 op_sel_hi:[0,1,0]
	v_fma_mix_f32 v12, v7, v188, v12 op_sel:[0,1,0] op_sel_hi:[0,1,0]
	v_fma_mix_f32 v12, v8, v189, v12 op_sel_hi:[0,1,0]
	v_fma_mix_f32 v12, v9, v189, v12 op_sel:[0,1,0] op_sel_hi:[0,1,0]
	v_fma_mix_f32 v135, v6, v160, v180 op_sel_hi:[0,1,0]
	v_fma_mix_f32 v135, v7, v160, v135 op_sel:[0,1,0] op_sel_hi:[0,1,0]
	v_add_f32_dpp v12, v12, v12 row_ror:1 row_mask:0xf bank_mask:0xf bound_ctrl:1
	v_fma_mix_f32 v135, v8, v161, v135 op_sel_hi:[0,1,0]
	v_fma_mix_f32 v135, v9, v161, v135 op_sel:[0,1,0] op_sel_hi:[0,1,0]
	v_add_f32_dpp v12, v12, v12 row_ror:2 row_mask:0xf bank_mask:0xf bound_ctrl:1
	v_pk_fma_f32 v[48:49], v[196:197], v[72:73], v[6:7] op_sel_hi:[1,0,1]
	v_pk_fma_f32 v[50:51], v[198:199], v[72:73], v[8:9] op_sel_hi:[1,0,1]
	v_add_f32_dpp v12, v12, v12 row_ror:4 row_mask:0xf bank_mask:0xf bound_ctrl:1
	v_add_f32_dpp v62, v62, v65 quad_perm:[1,0,3,2] row_mask:0xf bank_mask:0xf bound_ctrl:1
	v_cvt_pk_bf16_f32 v62, v62, v62
	v_add_f32_dpp v12, v12, v12 row_ror:8 row_mask:0xf bank_mask:0xf bound_ctrl:1
	v_pk_fma_f32 v[6:7], v[192:193], v[12:13], v[48:49] op_sel_hi:[1,0,1] neg_lo:[1,0,0] neg_hi:[1,0,0]
	v_pk_fma_f32 v[8:9], v[194:195], v[12:13], v[50:51] op_sel_hi:[1,0,1] neg_lo:[1,0,0] neg_hi:[1,0,0]
	ds_read_b128 v[110:113], v10 offset:36096
	ds_read_b128 v[106:109], v10 offset:35840
	ds_read_b128 v[118:121], v10 offset:36608
	ds_read_b128 v[114:117], v10 offset:36352
	v_fma_mix_f32 v12, v6, v204, v180 op_sel_hi:[0,1,0]
	v_fma_mix_f32 v12, v7, v204, v12 op_sel:[0,1,0] op_sel_hi:[0,1,0]
	v_fma_mix_f32 v12, v8, v205, v12 op_sel_hi:[0,1,0]
	v_fma_mix_f32 v12, v9, v205, v12 op_sel:[0,1,0] op_sel_hi:[0,1,0]
	v_fma_mix_f32 v136, v6, v190, v180 op_sel_hi:[0,1,0]
	v_fma_mix_f32 v136, v7, v190, v136 op_sel:[0,1,0] op_sel_hi:[0,1,0]
	v_add_f32_dpp v12, v12, v12 row_ror:1 row_mask:0xf bank_mask:0xf bound_ctrl:1
	v_fma_mix_f32 v136, v8, v191, v136 op_sel_hi:[0,1,0]
	v_fma_mix_f32 v136, v9, v191, v136 op_sel:[0,1,0] op_sel_hi:[0,1,0]
	v_add_f32_dpp v12, v12, v12 row_ror:2 row_mask:0xf bank_mask:0xf bound_ctrl:1
	v_pk_fma_f32 v[48:49], v[212:213], v[72:73], v[6:7] op_sel:[0,1,0]
	v_pk_fma_f32 v[50:51], v[214:215], v[72:73], v[8:9] op_sel:[0,1,0]
	v_add_f32_dpp v12, v12, v12 row_ror:4 row_mask:0xf bank_mask:0xf bound_ctrl:1
	global_store_short v[2:3], v62, off
	v_lshl_add_u64 v[2:3], v[2:3], 0, s[84:85]
	v_add_f32_dpp v12, v12, v12 row_ror:8 row_mask:0xf bank_mask:0xf bound_ctrl:1
	v_pk_fma_f32 v[6:7], v[208:209], v[12:13], v[48:49] op_sel_hi:[1,0,1] neg_lo:[1,0,0] neg_hi:[1,0,0]
	v_pk_fma_f32 v[8:9], v[210:211], v[12:13], v[50:51] op_sel_hi:[1,0,1] neg_lo:[1,0,0] neg_hi:[1,0,0]
	v_pk_mul_f32 v[6:7], v[6:7], v[200:201]
	v_pk_mul_f32 v[8:9], v[8:9], v[202:203]
	s_waitcnt lgkmcnt(0)
	ds_read_b128 v[142:145], v10 offset:37120
	ds_read_b128 v[150:153], v10 offset:37632
	ds_read_b128 v[146:149], v10 offset:37376
	v_fma_mix_f32 v12, v6, v20, v180 op_sel_hi:[0,1,0]
	v_fma_mix_f32 v12, v7, v20, v12 op_sel:[0,1,0] op_sel_hi:[0,1,0]
	v_fma_mix_f32 v12, v8, v21, v12 op_sel_hi:[0,1,0]
	v_fma_mix_f32 v12, v9, v21, v12 op_sel:[0,1,0] op_sel_hi:[0,1,0]
	v_fma_mix_f32 v137, v6, v206, v180 op_sel_hi:[0,1,0]
	v_fma_mix_f32 v137, v7, v206, v137 op_sel:[0,1,0] op_sel_hi:[0,1,0]
	v_add_f32_dpp v12, v12, v12 row_ror:1 row_mask:0xf bank_mask:0xf bound_ctrl:1
	v_fma_mix_f32 v137, v8, v207, v137 op_sel_hi:[0,1,0]
	v_fma_mix_f32 v137, v9, v207, v137 op_sel:[0,1,0] op_sel_hi:[0,1,0]
	v_add_f32_dpp v12, v12, v12 row_ror:2 row_mask:0xf bank_mask:0xf bound_ctrl:1
	v_pk_fma_f32 v[48:49], v[28:29], v[66:67], v[6:7] op_sel_hi:[1,0,1]
	v_pk_fma_f32 v[50:51], v[30:31], v[66:67], v[8:9] op_sel_hi:[1,0,1]
	v_add_f32_dpp v12, v12, v12 row_ror:4 row_mask:0xf bank_mask:0xf bound_ctrl:1
	s_nop 1
	v_add_f32_dpp v12, v12, v12 row_ror:8 row_mask:0xf bank_mask:0xf bound_ctrl:1
	v_pk_fma_f32 v[6:7], v[24:25], v[12:13], v[48:49] op_sel_hi:[1,0,1] neg_lo:[1,0,0] neg_hi:[1,0,0]
	v_pk_fma_f32 v[8:9], v[26:27], v[12:13], v[50:51] op_sel_hi:[1,0,1] neg_lo:[1,0,0] neg_hi:[1,0,0]
	ds_read_b128 v[158:161], v10 offset:38144
	ds_read_b128 v[166:169], v10 offset:38656
	ds_read_b128 v[162:165], v10 offset:38400
	ds_read_b128 v[70:73], v11 offset:2304
	v_fma_mix_f32 v12, v6, v36, v180 op_sel_hi:[0,1,0]
	v_fma_mix_f32 v12, v7, v36, v12 op_sel:[0,1,0] op_sel_hi:[0,1,0]
	v_fma_mix_f32 v12, v8, v37, v12 op_sel_hi:[0,1,0]
	v_fma_mix_f32 v12, v9, v37, v12 op_sel:[0,1,0] op_sel_hi:[0,1,0]
	v_fma_mix_f32 v52, v6, v22, v180 op_sel_hi:[0,1,0]
	v_fma_mix_f32 v52, v7, v22, v52 op_sel:[0,1,0] op_sel_hi:[0,1,0]
	v_add_f32_dpp v12, v12, v12 row_ror:1 row_mask:0xf bank_mask:0xf bound_ctrl:1
	v_fma_mix_f32 v52, v8, v23, v52 op_sel_hi:[0,1,0]
	v_fma_mix_f32 v52, v9, v23, v52 op_sel:[0,1,0] op_sel_hi:[0,1,0]
	v_add_f32_dpp v12, v12, v12 row_ror:2 row_mask:0xf bank_mask:0xf bound_ctrl:1
	v_pk_fma_f32 v[48:49], v[44:45], v[66:67], v[6:7] op_sel:[0,1,0]
	v_pk_fma_f32 v[50:51], v[46:47], v[66:67], v[8:9] op_sel:[0,1,0]
	v_add_f32_dpp v12, v12, v12 row_ror:4 row_mask:0xf bank_mask:0xf bound_ctrl:1
	v_add_f32_dpp v130, v130, v130 row_ror:8 row_mask:0xf bank_mask:0xc
	v_add_f32_dpp v130, v122, v122 row_ror:8 row_mask:0xf bank_mask:0x3
	v_add_f32_dpp v131, v131, v131 row_ror:8 row_mask:0xf bank_mask:0xc
	v_add_f32_dpp v12, v12, v12 row_ror:8 row_mask:0xf bank_mask:0xf bound_ctrl:1
	v_pk_fma_f32 v[6:7], v[40:41], v[12:13], v[48:49] op_sel_hi:[1,0,1] neg_lo:[1,0,0] neg_hi:[1,0,0]
	v_pk_fma_f32 v[8:9], v[42:43], v[12:13], v[50:51] op_sel_hi:[1,0,1] neg_lo:[1,0,0] neg_hi:[1,0,0]
	ds_read_b128 v[188:191], v10 offset:39168
	ds_read_b128 v[196:199], v10 offset:39680
	ds_read_b128 v[192:195], v10 offset:39424
	v_fma_mix_f32 v12, v6, v88, v180 op_sel_hi:[0,1,0]
	v_fma_mix_f32 v12, v7, v88, v12 op_sel:[0,1,0] op_sel_hi:[0,1,0]
	v_fma_mix_f32 v12, v8, v89, v12 op_sel_hi:[0,1,0]
	v_fma_mix_f32 v12, v9, v89, v12 op_sel:[0,1,0] op_sel_hi:[0,1,0]
	v_fma_mix_f32 v53, v6, v38, v180 op_sel_hi:[0,1,0]
	v_fma_mix_f32 v53, v7, v38, v53 op_sel:[0,1,0] op_sel_hi:[0,1,0]
	v_add_f32_dpp v12, v12, v12 row_ror:1 row_mask:0xf bank_mask:0xf bound_ctrl:1
	v_fma_mix_f32 v53, v8, v39, v53 op_sel_hi:[0,1,0]
	v_fma_mix_f32 v53, v9, v39, v53 op_sel:[0,1,0] op_sel_hi:[0,1,0]
	v_add_f32_dpp v12, v12, v12 row_ror:2 row_mask:0xf bank_mask:0xf bound_ctrl:1
	v_pk_fma_f32 v[48:49], v[96:97], v[68:69], v[6:7] op_sel_hi:[1,0,1]
	v_pk_fma_f32 v[50:51], v[98:99], v[68:69], v[8:9] op_sel_hi:[1,0,1]
	v_add_f32_dpp v12, v12, v12 row_ror:4 row_mask:0xf bank_mask:0xf bound_ctrl:1
	v_add_f32_dpp v131, v123, v123 row_ror:8 row_mask:0xf bank_mask:0x3
	v_add_f32_dpp v132, v132, v132 row_ror:8 row_mask:0xf bank_mask:0xc
	v_add_f32_dpp v132, v124, v124 row_ror:8 row_mask:0xf bank_mask:0x3
	v_add_f32_dpp v12, v12, v12 row_ror:8 row_mask:0xf bank_mask:0xf bound_ctrl:1
	v_pk_fma_f32 v[6:7], v[92:93], v[12:13], v[48:49] op_sel_hi:[1,0,1] neg_lo:[1,0,0] neg_hi:[1,0,0]
	v_pk_fma_f32 v[8:9], v[94:95], v[12:13], v[50:51] op_sel_hi:[1,0,1] neg_lo:[1,0,0] neg_hi:[1,0,0]
	ds_read_b128 v[204:207], v10 offset:40192
	ds_read_b128 v[200:203], v10 offset:39936
	ds_read_b128 v[212:215], v10 offset:40704
	ds_read_b128 v[208:211], v10 offset:40448
	v_fma_mix_f32 v12, v6, v110, v180 op_sel_hi:[0,1,0]
	v_fma_mix_f32 v12, v7, v110, v12 op_sel:[0,1,0] op_sel_hi:[0,1,0]
	v_fma_mix_f32 v12, v8, v111, v12 op_sel_hi:[0,1,0]
	v_fma_mix_f32 v12, v9, v111, v12 op_sel:[0,1,0] op_sel_hi:[0,1,0]
	v_fma_mix_f32 v54, v6, v90, v180 op_sel_hi:[0,1,0]
	v_fma_mix_f32 v54, v7, v90, v54 op_sel:[0,1,0] op_sel_hi:[0,1,0]
	v_add_f32_dpp v12, v12, v12 row_ror:1 row_mask:0xf bank_mask:0xf bound_ctrl:1
	v_fma_mix_f32 v54, v8, v91, v54 op_sel_hi:[0,1,0]
	v_fma_mix_f32 v54, v9, v91, v54 op_sel:[0,1,0] op_sel_hi:[0,1,0]
	v_add_f32_dpp v12, v12, v12 row_ror:2 row_mask:0xf bank_mask:0xf bound_ctrl:1
	v_pk_fma_f32 v[48:49], v[118:119], v[68:69], v[6:7] op_sel:[0,1,0]
	v_pk_fma_f32 v[50:51], v[120:121], v[68:69], v[8:9] op_sel:[0,1,0]
	v_add_f32_dpp v12, v12, v12 row_ror:4 row_mask:0xf bank_mask:0xf bound_ctrl:1
	v_add_f32_dpp v133, v133, v133 row_ror:8 row_mask:0xf bank_mask:0xc
	v_add_f32_dpp v133, v125, v125 row_ror:8 row_mask:0xf bank_mask:0x3
	v_add_f32_dpp v134, v134, v134 row_ror:8 row_mask:0xf bank_mask:0xc
	v_add_f32_dpp v12, v12, v12 row_ror:8 row_mask:0xf bank_mask:0xf bound_ctrl:1
	v_pk_fma_f32 v[6:7], v[114:115], v[12:13], v[48:49] op_sel_hi:[1,0,1] neg_lo:[1,0,0] neg_hi:[1,0,0]
	v_pk_fma_f32 v[8:9], v[116:117], v[12:13], v[50:51] op_sel_hi:[1,0,1] neg_lo:[1,0,0] neg_hi:[1,0,0]
	v_pk_mul_f32 v[6:7], v[6:7], v[106:107]
	v_pk_mul_f32 v[8:9], v[8:9], v[108:109]
	s_waitcnt lgkmcnt(0)
	ds_read_b128 v[20:23], v10 offset:41216
	ds_read_b128 v[28:31], v10 offset:41728
	ds_read_b128 v[24:27], v10 offset:41472
	v_fma_mix_f32 v12, v6, v142, v180 op_sel_hi:[0,1,0]
	v_fma_mix_f32 v12, v7, v142, v12 op_sel:[0,1,0] op_sel_hi:[0,1,0]
	v_fma_mix_f32 v12, v8, v143, v12 op_sel_hi:[0,1,0]
	v_fma_mix_f32 v12, v9, v143, v12 op_sel:[0,1,0] op_sel_hi:[0,1,0]
	v_fma_mix_f32 v55, v6, v112, v180 op_sel_hi:[0,1,0]
	v_fma_mix_f32 v55, v7, v112, v55 op_sel:[0,1,0] op_sel_hi:[0,1,0]
	v_add_f32_dpp v12, v12, v12 row_ror:1 row_mask:0xf bank_mask:0xf bound_ctrl:1
	v_fma_mix_f32 v55, v8, v113, v55 op_sel_hi:[0,1,0]
	v_fma_mix_f32 v55, v9, v113, v55 op_sel:[0,1,0] op_sel_hi:[0,1,0]
	v_add_f32_dpp v12, v12, v12 row_ror:2 row_mask:0xf bank_mask:0xf bound_ctrl:1
	v_pk_fma_f32 v[48:49], v[150:151], v[70:71], v[6:7] op_sel_hi:[1,0,1]
	v_pk_fma_f32 v[50:51], v[152:153], v[70:71], v[8:9] op_sel_hi:[1,0,1]
	v_add_f32_dpp v12, v12, v12 row_ror:4 row_mask:0xf bank_mask:0xf bound_ctrl:1
	v_add_f32_dpp v134, v126, v126 row_ror:8 row_mask:0xf bank_mask:0x3
	v_add_f32_dpp v135, v135, v135 row_ror:8 row_mask:0xf bank_mask:0xc
	v_add_f32_dpp v135, v127, v127 row_ror:8 row_mask:0xf bank_mask:0x3
	v_add_f32_dpp v12, v12, v12 row_ror:8 row_mask:0xf bank_mask:0xf bound_ctrl:1
	v_pk_fma_f32 v[6:7], v[146:147], v[12:13], v[48:49] op_sel_hi:[1,0,1] neg_lo:[1,0,0] neg_hi:[1,0,0]
	v_pk_fma_f32 v[8:9], v[148:149], v[12:13], v[50:51] op_sel_hi:[1,0,1] neg_lo:[1,0,0] neg_hi:[1,0,0]
	ds_read_b128 v[36:39], v10 offset:42240
	ds_read_b128 v[44:47], v10 offset:42752
	ds_read_b128 v[40:43], v10 offset:42496
	ds_read_b128 v[66:69], v11 offset:2560
	v_fma_mix_f32 v12, v6, v158, v180 op_sel_hi:[0,1,0]
	v_fma_mix_f32 v12, v7, v158, v12 op_sel:[0,1,0] op_sel_hi:[0,1,0]
	v_fma_mix_f32 v12, v8, v159, v12 op_sel_hi:[0,1,0]
	v_fma_mix_f32 v12, v9, v159, v12 op_sel:[0,1,0] op_sel_hi:[0,1,0]
	v_fma_mix_f32 v56, v6, v144, v180 op_sel_hi:[0,1,0]
	v_fma_mix_f32 v56, v7, v144, v56 op_sel:[0,1,0] op_sel_hi:[0,1,0]
	v_add_f32_dpp v12, v12, v12 row_ror:1 row_mask:0xf bank_mask:0xf bound_ctrl:1
	v_fma_mix_f32 v56, v8, v145, v56 op_sel_hi:[0,1,0]
	v_fma_mix_f32 v56, v9, v145, v56 op_sel:[0,1,0] op_sel_hi:[0,1,0]
	v_add_f32_dpp v12, v12, v12 row_ror:2 row_mask:0xf bank_mask:0xf bound_ctrl:1
	v_pk_fma_f32 v[48:49], v[166:167], v[70:71], v[6:7] op_sel:[0,1,0]
	v_pk_fma_f32 v[50:51], v[168:169], v[70:71], v[8:9] op_sel:[0,1,0]
	v_add_f32_dpp v12, v12, v12 row_ror:4 row_mask:0xf bank_mask:0xf bound_ctrl:1
	v_add_f32_dpp v136, v136, v136 row_ror:8 row_mask:0xf bank_mask:0xc
	v_add_f32_dpp v136, v128, v128 row_ror:8 row_mask:0xf bank_mask:0x3
	v_add_f32_dpp v12, v12, v12 row_ror:8 row_mask:0xf bank_mask:0xf bound_ctrl:1
	v_pk_fma_f32 v[6:7], v[162:163], v[12:13], v[48:49] op_sel_hi:[1,0,1] neg_lo:[1,0,0] neg_hi:[1,0,0]
	v_pk_fma_f32 v[8:9], v[164:165], v[12:13], v[50:51] op_sel_hi:[1,0,1] neg_lo:[1,0,0] neg_hi:[1,0,0]
	ds_read_b128 v[88:91], v10 offset:43264
	ds_read_b128 v[96:99], v10 offset:43776
	ds_read_b128 v[92:95], v10 offset:43520
	v_fma_mix_f32 v12, v6, v188, v180 op_sel_hi:[0,1,0]
	v_fma_mix_f32 v12, v7, v188, v12 op_sel:[0,1,0] op_sel_hi:[0,1,0]
	v_fma_mix_f32 v12, v8, v189, v12 op_sel_hi:[0,1,0]
	v_fma_mix_f32 v12, v9, v189, v12 op_sel:[0,1,0] op_sel_hi:[0,1,0]
	v_fma_mix_f32 v57, v6, v160, v180 op_sel_hi:[0,1,0]
	v_fma_mix_f32 v57, v7, v160, v57 op_sel:[0,1,0] op_sel_hi:[0,1,0]
	v_add_f32_dpp v12, v12, v12 row_ror:1 row_mask:0xf bank_mask:0xf bound_ctrl:1
	v_fma_mix_f32 v57, v8, v161, v57 op_sel_hi:[0,1,0]
	v_fma_mix_f32 v57, v9, v161, v57 op_sel:[0,1,0] op_sel_hi:[0,1,0]
	v_add_f32_dpp v12, v12, v12 row_ror:2 row_mask:0xf bank_mask:0xf bound_ctrl:1
	v_pk_fma_f32 v[48:49], v[196:197], v[72:73], v[6:7] op_sel_hi:[1,0,1]
	v_pk_fma_f32 v[50:51], v[198:199], v[72:73], v[8:9] op_sel_hi:[1,0,1]
	v_add_f32_dpp v12, v12, v12 row_ror:4 row_mask:0xf bank_mask:0xf bound_ctrl:1
	v_add_f32_dpp v137, v137, v137 row_ror:8 row_mask:0xf bank_mask:0xc
	v_add_f32_dpp v137, v129, v129 row_ror:8 row_mask:0xf bank_mask:0x3
	v_add_f32_dpp v12, v12, v12 row_ror:8 row_mask:0xf bank_mask:0xf bound_ctrl:1
	v_pk_fma_f32 v[6:7], v[192:193], v[12:13], v[48:49] op_sel_hi:[1,0,1] neg_lo:[1,0,0] neg_hi:[1,0,0]
	v_pk_fma_f32 v[8:9], v[194:195], v[12:13], v[50:51] op_sel_hi:[1,0,1] neg_lo:[1,0,0] neg_hi:[1,0,0]
	ds_read_b128 v[110:113], v10 offset:44288
	ds_read_b128 v[106:109], v10 offset:44032
	ds_read_b128 v[118:121], v10 offset:44800
	ds_read_b128 v[114:117], v10 offset:44544
	v_fma_mix_f32 v12, v6, v204, v180 op_sel_hi:[0,1,0]
	v_fma_mix_f32 v12, v7, v204, v12 op_sel:[0,1,0] op_sel_hi:[0,1,0]
	v_fma_mix_f32 v12, v8, v205, v12 op_sel_hi:[0,1,0]
	v_fma_mix_f32 v12, v9, v205, v12 op_sel:[0,1,0] op_sel_hi:[0,1,0]
	v_fma_mix_f32 v81, v6, v190, v180 op_sel_hi:[0,1,0]
	v_fma_mix_f32 v81, v7, v190, v81 op_sel:[0,1,0] op_sel_hi:[0,1,0]
	v_add_f32_dpp v12, v12, v12 row_ror:1 row_mask:0xf bank_mask:0xf bound_ctrl:1
	v_fma_mix_f32 v81, v8, v191, v81 op_sel_hi:[0,1,0]
	v_fma_mix_f32 v81, v9, v191, v81 op_sel:[0,1,0] op_sel_hi:[0,1,0]
	v_add_f32_dpp v12, v12, v12 row_ror:2 row_mask:0xf bank_mask:0xf bound_ctrl:1
	v_pk_fma_f32 v[48:49], v[212:213], v[72:73], v[6:7] op_sel:[0,1,0]
	v_pk_fma_f32 v[50:51], v[214:215], v[72:73], v[8:9] op_sel:[0,1,0]
	v_add_f32_dpp v12, v12, v12 row_ror:4 row_mask:0xf bank_mask:0xf bound_ctrl:1
	v_add_f32_dpp v134, v134, v134 row_ror:4 row_mask:0xf bank_mask:0xa
	v_add_f32_dpp v134, v130, v130 row_ror:12 row_mask:0xf bank_mask:0x5
	v_add_f32_dpp v135, v135, v135 row_ror:4 row_mask:0xf bank_mask:0xa
	v_add_f32_dpp v12, v12, v12 row_ror:8 row_mask:0xf bank_mask:0xf bound_ctrl:1
	v_pk_fma_f32 v[6:7], v[208:209], v[12:13], v[48:49] op_sel_hi:[1,0,1] neg_lo:[1,0,0] neg_hi:[1,0,0]
	v_pk_fma_f32 v[8:9], v[210:211], v[12:13], v[50:51] op_sel_hi:[1,0,1] neg_lo:[1,0,0] neg_hi:[1,0,0]
	v_pk_mul_f32 v[6:7], v[6:7], v[200:201]
	v_pk_mul_f32 v[8:9], v[8:9], v[202:203]
	s_waitcnt lgkmcnt(0)
	ds_read_b128 v[142:145], v10 offset:45312
	ds_read_b128 v[150:153], v10 offset:45824
	ds_read_b128 v[146:149], v10 offset:45568
	v_fma_mix_f32 v12, v6, v20, v180 op_sel_hi:[0,1,0]
	v_fma_mix_f32 v12, v7, v20, v12 op_sel:[0,1,0] op_sel_hi:[0,1,0]
	v_fma_mix_f32 v12, v8, v21, v12 op_sel_hi:[0,1,0]
	v_fma_mix_f32 v12, v9, v21, v12 op_sel:[0,1,0] op_sel_hi:[0,1,0]
	v_fma_mix_f32 v82, v6, v206, v180 op_sel_hi:[0,1,0]
	v_fma_mix_f32 v82, v7, v206, v82 op_sel:[0,1,0] op_sel_hi:[0,1,0]
	v_add_f32_dpp v12, v12, v12 row_ror:1 row_mask:0xf bank_mask:0xf bound_ctrl:1
	v_fma_mix_f32 v82, v8, v207, v82 op_sel_hi:[0,1,0]
	v_fma_mix_f32 v82, v9, v207, v82 op_sel:[0,1,0] op_sel_hi:[0,1,0]
	v_add_f32_dpp v12, v12, v12 row_ror:2 row_mask:0xf bank_mask:0xf bound_ctrl:1
	v_pk_fma_f32 v[48:49], v[28:29], v[66:67], v[6:7] op_sel_hi:[1,0,1]
	v_pk_fma_f32 v[50:51], v[30:31], v[66:67], v[8:9] op_sel_hi:[1,0,1]
	v_add_f32_dpp v12, v12, v12 row_ror:4 row_mask:0xf bank_mask:0xf bound_ctrl:1
	v_add_f32_dpp v135, v131, v131 row_ror:12 row_mask:0xf bank_mask:0x5
	v_add_f32_dpp v136, v136, v136 row_ror:4 row_mask:0xf bank_mask:0xa
	v_add_f32_dpp v136, v132, v132 row_ror:12 row_mask:0xf bank_mask:0x5
	v_add_f32_dpp v12, v12, v12 row_ror:8 row_mask:0xf bank_mask:0xf bound_ctrl:1
	v_pk_fma_f32 v[6:7], v[24:25], v[12:13], v[48:49] op_sel_hi:[1,0,1] neg_lo:[1,0,0] neg_hi:[1,0,0]
	v_pk_fma_f32 v[8:9], v[26:27], v[12:13], v[50:51] op_sel_hi:[1,0,1] neg_lo:[1,0,0] neg_hi:[1,0,0]
	ds_read_b128 v[158:161], v10 offset:46336
	ds_read_b128 v[166:169], v10 offset:46848
	ds_read_b128 v[162:165], v10 offset:46592
	ds_read_b128 v[70:73], v11 offset:2816
	v_fma_mix_f32 v12, v6, v36, v180 op_sel_hi:[0,1,0]
	v_fma_mix_f32 v12, v7, v36, v12 op_sel:[0,1,0] op_sel_hi:[0,1,0]
	v_fma_mix_f32 v12, v8, v37, v12 op_sel_hi:[0,1,0]
	v_fma_mix_f32 v12, v9, v37, v12 op_sel:[0,1,0] op_sel_hi:[0,1,0]
	v_fma_mix_f32 v83, v6, v22, v180 op_sel_hi:[0,1,0]
	v_fma_mix_f32 v83, v7, v22, v83 op_sel:[0,1,0] op_sel_hi:[0,1,0]
	v_add_f32_dpp v12, v12, v12 row_ror:1 row_mask:0xf bank_mask:0xf bound_ctrl:1
	v_fma_mix_f32 v83, v8, v23, v83 op_sel_hi:[0,1,0]
	v_fma_mix_f32 v83, v9, v23, v83 op_sel:[0,1,0] op_sel_hi:[0,1,0]
	v_add_f32_dpp v12, v12, v12 row_ror:2 row_mask:0xf bank_mask:0xf bound_ctrl:1
	v_pk_fma_f32 v[48:49], v[44:45], v[66:67], v[6:7] op_sel:[0,1,0]
	v_pk_fma_f32 v[50:51], v[46:47], v[66:67], v[8:9] op_sel:[0,1,0]
	v_add_f32_dpp v12, v12, v12 row_ror:4 row_mask:0xf bank_mask:0xf bound_ctrl:1
	v_add_f32_dpp v137, v137, v137 row_ror:4 row_mask:0xf bank_mask:0xa
	v_add_f32_dpp v137, v133, v133 row_ror:12 row_mask:0xf bank_mask:0x5
	v_add_f32_dpp v12, v12, v12 row_ror:8 row_mask:0xf bank_mask:0xf bound_ctrl:1
	v_pk_fma_f32 v[6:7], v[40:41], v[12:13], v[48:49] op_sel_hi:[1,0,1] neg_lo:[1,0,0] neg_hi:[1,0,0]
	v_pk_fma_f32 v[8:9], v[42:43], v[12:13], v[50:51] op_sel_hi:[1,0,1] neg_lo:[1,0,0] neg_hi:[1,0,0]
	ds_read_b128 v[188:191], v10 offset:47360
	ds_read_b128 v[196:199], v10 offset:47872
	ds_read_b128 v[192:195], v10 offset:47616
	v_fma_mix_f32 v12, v6, v88, v180 op_sel_hi:[0,1,0]
	v_fma_mix_f32 v12, v7, v88, v12 op_sel:[0,1,0] op_sel_hi:[0,1,0]
	v_fma_mix_f32 v12, v8, v89, v12 op_sel_hi:[0,1,0]
	v_fma_mix_f32 v12, v9, v89, v12 op_sel:[0,1,0] op_sel_hi:[0,1,0]
	v_fma_mix_f32 v100, v6, v38, v180 op_sel_hi:[0,1,0]
	v_fma_mix_f32 v100, v7, v38, v100 op_sel:[0,1,0] op_sel_hi:[0,1,0]
	v_add_f32_dpp v12, v12, v12 row_ror:1 row_mask:0xf bank_mask:0xf bound_ctrl:1
	v_fma_mix_f32 v100, v8, v39, v100 op_sel_hi:[0,1,0]
	v_fma_mix_f32 v100, v9, v39, v100 op_sel:[0,1,0] op_sel_hi:[0,1,0]
	v_add_f32_dpp v12, v12, v12 row_ror:2 row_mask:0xf bank_mask:0xf bound_ctrl:1
	v_pk_fma_f32 v[48:49], v[96:97], v[68:69], v[6:7] op_sel_hi:[1,0,1]
	v_pk_fma_f32 v[50:51], v[98:99], v[68:69], v[8:9] op_sel_hi:[1,0,1]
	v_add_f32_dpp v12, v12, v12 row_ror:4 row_mask:0xf bank_mask:0xf bound_ctrl:1
	v_cndmask_b32_e64 v62, v136, v134, s[38:39]
	v_cndmask_b32_e64 v63, v134, v136, s[38:39]
	v_add_f32_dpp v12, v12, v12 row_ror:8 row_mask:0xf bank_mask:0xf bound_ctrl:1
	v_pk_fma_f32 v[6:7], v[92:93], v[12:13], v[48:49] op_sel_hi:[1,0,1] neg_lo:[1,0,0] neg_hi:[1,0,0]
	v_pk_fma_f32 v[8:9], v[94:95], v[12:13], v[50:51] op_sel_hi:[1,0,1] neg_lo:[1,0,0] neg_hi:[1,0,0]
	ds_read_b128 v[204:207], v10 offset:48384
	ds_read_b128 v[200:203], v10 offset:48128
	ds_read_b128 v[212:215], v10 offset:48896
	ds_read_b128 v[208:211], v10 offset:48640
	v_fma_mix_f32 v12, v6, v110, v180 op_sel_hi:[0,1,0]
	v_fma_mix_f32 v12, v7, v110, v12 op_sel:[0,1,0] op_sel_hi:[0,1,0]
	v_fma_mix_f32 v12, v8, v111, v12 op_sel_hi:[0,1,0]
	v_fma_mix_f32 v12, v9, v111, v12 op_sel:[0,1,0] op_sel_hi:[0,1,0]
	v_fma_mix_f32 v101, v6, v90, v180 op_sel_hi:[0,1,0]
	v_fma_mix_f32 v101, v7, v90, v101 op_sel:[0,1,0] op_sel_hi:[0,1,0]
	v_add_f32_dpp v12, v12, v12 row_ror:1 row_mask:0xf bank_mask:0xf bound_ctrl:1
	v_fma_mix_f32 v101, v8, v91, v101 op_sel_hi:[0,1,0]
	v_fma_mix_f32 v101, v9, v91, v101 op_sel:[0,1,0] op_sel_hi:[0,1,0]
	v_add_f32_dpp v12, v12, v12 row_ror:2 row_mask:0xf bank_mask:0xf bound_ctrl:1
	v_pk_fma_f32 v[48:49], v[118:119], v[68:69], v[6:7] op_sel:[0,1,0]
	v_pk_fma_f32 v[50:51], v[120:121], v[68:69], v[8:9] op_sel:[0,1,0]
	v_add_f32_dpp v12, v12, v12 row_ror:4 row_mask:0xf bank_mask:0xf bound_ctrl:1
	v_cndmask_b32_e64 v64, v137, v135, s[38:39]
	v_cndmask_b32_e64 v65, v135, v137, s[38:39]
	v_add_f32_dpp v12, v12, v12 row_ror:8 row_mask:0xf bank_mask:0xf bound_ctrl:1
	v_pk_fma_f32 v[6:7], v[114:115], v[12:13], v[48:49] op_sel_hi:[1,0,1] neg_lo:[1,0,0] neg_hi:[1,0,0]
	v_pk_fma_f32 v[8:9], v[116:117], v[12:13], v[50:51] op_sel_hi:[1,0,1] neg_lo:[1,0,0] neg_hi:[1,0,0]
	v_pk_mul_f32 v[6:7], v[6:7], v[106:107]
	v_pk_mul_f32 v[8:9], v[8:9], v[108:109]
	s_waitcnt lgkmcnt(0)
	ds_read_b128 v[20:23], v10 offset:49408
	ds_read_b128 v[28:31], v10 offset:49920
	ds_read_b128 v[24:27], v10 offset:49664
	v_fma_mix_f32 v12, v6, v142, v180 op_sel_hi:[0,1,0]
	v_fma_mix_f32 v12, v7, v142, v12 op_sel:[0,1,0] op_sel_hi:[0,1,0]
	v_fma_mix_f32 v12, v8, v143, v12 op_sel_hi:[0,1,0]
	v_fma_mix_f32 v12, v9, v143, v12 op_sel:[0,1,0] op_sel_hi:[0,1,0]
	v_fma_mix_f32 v102, v6, v112, v180 op_sel_hi:[0,1,0]
	v_fma_mix_f32 v102, v7, v112, v102 op_sel:[0,1,0] op_sel_hi:[0,1,0]
	v_add_f32_dpp v12, v12, v12 row_ror:1 row_mask:0xf bank_mask:0xf bound_ctrl:1
	v_fma_mix_f32 v102, v8, v113, v102 op_sel_hi:[0,1,0]
	v_fma_mix_f32 v102, v9, v113, v102 op_sel:[0,1,0] op_sel_hi:[0,1,0]
	v_add_f32_dpp v12, v12, v12 row_ror:2 row_mask:0xf bank_mask:0xf bound_ctrl:1
	v_pk_fma_f32 v[48:49], v[150:151], v[70:71], v[6:7] op_sel_hi:[1,0,1]
	v_pk_fma_f32 v[50:51], v[152:153], v[70:71], v[8:9] op_sel_hi:[1,0,1]
	v_add_f32_dpp v12, v12, v12 row_ror:4 row_mask:0xf bank_mask:0xf bound_ctrl:1
	v_add_f32_dpp v62, v63, v62 quad_perm:[2,3,0,1] row_mask:0xf bank_mask:0xf bound_ctrl:1
	v_add_f32_dpp v63, v65, v64 quad_perm:[2,3,0,1] row_mask:0xf bank_mask:0xf bound_ctrl:1
	v_add_f32_dpp v12, v12, v12 row_ror:8 row_mask:0xf bank_mask:0xf bound_ctrl:1
	v_pk_fma_f32 v[6:7], v[146:147], v[12:13], v[48:49] op_sel_hi:[1,0,1] neg_lo:[1,0,0] neg_hi:[1,0,0]
	v_pk_fma_f32 v[8:9], v[148:149], v[12:13], v[50:51] op_sel_hi:[1,0,1] neg_lo:[1,0,0] neg_hi:[1,0,0]
	ds_read_b128 v[36:39], v10 offset:50432
	ds_read_b128 v[44:47], v10 offset:50944
	ds_read_b128 v[40:43], v10 offset:50688
	ds_read_b128 v[66:69], v11 offset:3072
	v_fma_mix_f32 v12, v6, v158, v180 op_sel_hi:[0,1,0]
	v_fma_mix_f32 v12, v7, v158, v12 op_sel:[0,1,0] op_sel_hi:[0,1,0]
	v_fma_mix_f32 v12, v8, v159, v12 op_sel_hi:[0,1,0]
	v_fma_mix_f32 v12, v9, v159, v12 op_sel:[0,1,0] op_sel_hi:[0,1,0]
	v_fma_mix_f32 v103, v6, v144, v180 op_sel_hi:[0,1,0]
	v_fma_mix_f32 v103, v7, v144, v103 op_sel:[0,1,0] op_sel_hi:[0,1,0]
	v_add_f32_dpp v12, v12, v12 row_ror:1 row_mask:0xf bank_mask:0xf bound_ctrl:1
	v_fma_mix_f32 v103, v8, v145, v103 op_sel_hi:[0,1,0]
	v_fma_mix_f32 v103, v9, v145, v103 op_sel:[0,1,0] op_sel_hi:[0,1,0]
	v_add_f32_dpp v12, v12, v12 row_ror:2 row_mask:0xf bank_mask:0xf bound_ctrl:1
	v_pk_fma_f32 v[48:49], v[166:167], v[70:71], v[6:7] op_sel:[0,1,0]
	v_pk_fma_f32 v[50:51], v[168:169], v[70:71], v[8:9] op_sel:[0,1,0]
	v_add_f32_dpp v12, v12, v12 row_ror:4 row_mask:0xf bank_mask:0xf bound_ctrl:1
	v_cndmask_b32_e64 v65, v63, v62, s[40:41]
	v_cndmask_b32_e64 v62, v62, v63, s[40:41]
	v_add_f32_dpp v12, v12, v12 row_ror:8 row_mask:0xf bank_mask:0xf bound_ctrl:1
	v_pk_fma_f32 v[6:7], v[162:163], v[12:13], v[48:49] op_sel_hi:[1,0,1] neg_lo:[1,0,0] neg_hi:[1,0,0]
	v_pk_fma_f32 v[8:9], v[164:165], v[12:13], v[50:51] op_sel_hi:[1,0,1] neg_lo:[1,0,0] neg_hi:[1,0,0]
	ds_read_b128 v[88:91], v10 offset:51456
	ds_read_b128 v[96:99], v10 offset:51968
	ds_read_b128 v[92:95], v10 offset:51712
	v_fma_mix_f32 v12, v6, v188, v180 op_sel_hi:[0,1,0]
	v_fma_mix_f32 v12, v7, v188, v12 op_sel:[0,1,0] op_sel_hi:[0,1,0]
	v_fma_mix_f32 v12, v8, v189, v12 op_sel_hi:[0,1,0]
	v_fma_mix_f32 v12, v9, v189, v12 op_sel:[0,1,0] op_sel_hi:[0,1,0]
	v_fma_mix_f32 v104, v6, v160, v180 op_sel_hi:[0,1,0]
	v_fma_mix_f32 v104, v7, v160, v104 op_sel:[0,1,0] op_sel_hi:[0,1,0]
	v_add_f32_dpp v12, v12, v12 row_ror:1 row_mask:0xf bank_mask:0xf bound_ctrl:1
	v_fma_mix_f32 v104, v8, v161, v104 op_sel_hi:[0,1,0]
	v_fma_mix_f32 v104, v9, v161, v104 op_sel:[0,1,0] op_sel_hi:[0,1,0]
	v_add_f32_dpp v12, v12, v12 row_ror:2 row_mask:0xf bank_mask:0xf bound_ctrl:1
	v_pk_fma_f32 v[48:49], v[196:197], v[72:73], v[6:7] op_sel_hi:[1,0,1]
	v_pk_fma_f32 v[50:51], v[198:199], v[72:73], v[8:9] op_sel_hi:[1,0,1]
	v_add_f32_dpp v12, v12, v12 row_ror:4 row_mask:0xf bank_mask:0xf bound_ctrl:1
	v_add_f32_dpp v62, v62, v65 quad_perm:[1,0,3,2] row_mask:0xf bank_mask:0xf bound_ctrl:1
	v_cvt_pk_bf16_f32 v62, v62, v62
	v_add_f32_dpp v12, v12, v12 row_ror:8 row_mask:0xf bank_mask:0xf bound_ctrl:1
	v_pk_fma_f32 v[6:7], v[192:193], v[12:13], v[48:49] op_sel_hi:[1,0,1] neg_lo:[1,0,0] neg_hi:[1,0,0]
	v_pk_fma_f32 v[8:9], v[194:195], v[12:13], v[50:51] op_sel_hi:[1,0,1] neg_lo:[1,0,0] neg_hi:[1,0,0]
	ds_read_b128 v[110:113], v10 offset:52480
	ds_read_b128 v[106:109], v10 offset:52224
	ds_read_b128 v[118:121], v10 offset:52992
	ds_read_b128 v[114:117], v10 offset:52736
	v_fma_mix_f32 v12, v6, v204, v180 op_sel_hi:[0,1,0]
	v_fma_mix_f32 v12, v7, v204, v12 op_sel:[0,1,0] op_sel_hi:[0,1,0]
	v_fma_mix_f32 v12, v8, v205, v12 op_sel_hi:[0,1,0]
	v_fma_mix_f32 v12, v9, v205, v12 op_sel:[0,1,0] op_sel_hi:[0,1,0]
	v_fma_mix_f32 v105, v6, v190, v180 op_sel_hi:[0,1,0]
	v_fma_mix_f32 v105, v7, v190, v105 op_sel:[0,1,0] op_sel_hi:[0,1,0]
	v_add_f32_dpp v12, v12, v12 row_ror:1 row_mask:0xf bank_mask:0xf bound_ctrl:1
	v_fma_mix_f32 v105, v8, v191, v105 op_sel_hi:[0,1,0]
	v_fma_mix_f32 v105, v9, v191, v105 op_sel:[0,1,0] op_sel_hi:[0,1,0]
	v_add_f32_dpp v12, v12, v12 row_ror:2 row_mask:0xf bank_mask:0xf bound_ctrl:1
	v_pk_fma_f32 v[48:49], v[212:213], v[72:73], v[6:7] op_sel:[0,1,0]
	v_pk_fma_f32 v[50:51], v[214:215], v[72:73], v[8:9] op_sel:[0,1,0]
	v_add_f32_dpp v12, v12, v12 row_ror:4 row_mask:0xf bank_mask:0xf bound_ctrl:1
	global_store_short v[2:3], v62, off
	v_lshl_add_u64 v[2:3], v[2:3], 0, s[84:85]
	v_add_f32_dpp v12, v12, v12 row_ror:8 row_mask:0xf bank_mask:0xf bound_ctrl:1
	v_pk_fma_f32 v[6:7], v[208:209], v[12:13], v[48:49] op_sel_hi:[1,0,1] neg_lo:[1,0,0] neg_hi:[1,0,0]
	v_pk_fma_f32 v[8:9], v[210:211], v[12:13], v[50:51] op_sel_hi:[1,0,1] neg_lo:[1,0,0] neg_hi:[1,0,0]
	v_pk_mul_f32 v[6:7], v[6:7], v[200:201]
	v_pk_mul_f32 v[8:9], v[8:9], v[202:203]
	s_waitcnt lgkmcnt(0)
	ds_read_b128 v[142:145], v10 offset:53504
	ds_read_b128 v[150:153], v10 offset:54016
	ds_read_b128 v[146:149], v10 offset:53760
	v_fma_mix_f32 v12, v6, v20, v180 op_sel_hi:[0,1,0]
	v_fma_mix_f32 v12, v7, v20, v12 op_sel:[0,1,0] op_sel_hi:[0,1,0]
	v_fma_mix_f32 v12, v8, v21, v12 op_sel_hi:[0,1,0]
	v_fma_mix_f32 v12, v9, v21, v12 op_sel:[0,1,0] op_sel_hi:[0,1,0]
	v_fma_mix_f32 v61, v6, v206, v180 op_sel_hi:[0,1,0]
	v_fma_mix_f32 v61, v7, v206, v61 op_sel:[0,1,0] op_sel_hi:[0,1,0]
	v_add_f32_dpp v12, v12, v12 row_ror:1 row_mask:0xf bank_mask:0xf bound_ctrl:1
	v_fma_mix_f32 v61, v8, v207, v61 op_sel_hi:[0,1,0]
	v_fma_mix_f32 v61, v9, v207, v61 op_sel:[0,1,0] op_sel_hi:[0,1,0]
	v_add_f32_dpp v12, v12, v12 row_ror:2 row_mask:0xf bank_mask:0xf bound_ctrl:1
	v_pk_fma_f32 v[48:49], v[28:29], v[66:67], v[6:7] op_sel_hi:[1,0,1]
	v_pk_fma_f32 v[50:51], v[30:31], v[66:67], v[8:9] op_sel_hi:[1,0,1]
	v_add_f32_dpp v12, v12, v12 row_ror:4 row_mask:0xf bank_mask:0xf bound_ctrl:1
	s_nop 1
	v_add_f32_dpp v12, v12, v12 row_ror:8 row_mask:0xf bank_mask:0xf bound_ctrl:1
	v_pk_fma_f32 v[6:7], v[24:25], v[12:13], v[48:49] op_sel_hi:[1,0,1] neg_lo:[1,0,0] neg_hi:[1,0,0]
	v_pk_fma_f32 v[8:9], v[26:27], v[12:13], v[50:51] op_sel_hi:[1,0,1] neg_lo:[1,0,0] neg_hi:[1,0,0]
	ds_read_b128 v[158:161], v10 offset:54528
	ds_read_b128 v[166:169], v10 offset:55040
	ds_read_b128 v[162:165], v10 offset:54784
	ds_read_b128 v[70:73], v11 offset:3328
	v_fma_mix_f32 v12, v6, v36, v180 op_sel_hi:[0,1,0]
	v_fma_mix_f32 v12, v7, v36, v12 op_sel:[0,1,0] op_sel_hi:[0,1,0]
	v_fma_mix_f32 v12, v8, v37, v12 op_sel_hi:[0,1,0]
	v_fma_mix_f32 v12, v9, v37, v12 op_sel:[0,1,0] op_sel_hi:[0,1,0]
	v_fma_mix_f32 v122, v6, v22, v180 op_sel_hi:[0,1,0]
	v_fma_mix_f32 v122, v7, v22, v122 op_sel:[0,1,0] op_sel_hi:[0,1,0]
	v_add_f32_dpp v12, v12, v12 row_ror:1 row_mask:0xf bank_mask:0xf bound_ctrl:1
	v_fma_mix_f32 v122, v8, v23, v122 op_sel_hi:[0,1,0]
	v_fma_mix_f32 v122, v9, v23, v122 op_sel:[0,1,0] op_sel_hi:[0,1,0]
	v_add_f32_dpp v12, v12, v12 row_ror:2 row_mask:0xf bank_mask:0xf bound_ctrl:1
	v_pk_fma_f32 v[48:49], v[44:45], v[66:67], v[6:7] op_sel:[0,1,0]
	v_pk_fma_f32 v[50:51], v[46:47], v[66:67], v[8:9] op_sel:[0,1,0]
	v_add_f32_dpp v12, v12, v12 row_ror:4 row_mask:0xf bank_mask:0xf bound_ctrl:1
	v_add_f32_dpp v83, v83, v83 row_ror:8 row_mask:0xf bank_mask:0xc
	v_add_f32_dpp v83, v52, v52 row_ror:8 row_mask:0xf bank_mask:0x3
	v_add_f32_dpp v100, v100, v100 row_ror:8 row_mask:0xf bank_mask:0xc
	v_add_f32_dpp v12, v12, v12 row_ror:8 row_mask:0xf bank_mask:0xf bound_ctrl:1
	v_pk_fma_f32 v[6:7], v[40:41], v[12:13], v[48:49] op_sel_hi:[1,0,1] neg_lo:[1,0,0] neg_hi:[1,0,0]
	v_pk_fma_f32 v[8:9], v[42:43], v[12:13], v[50:51] op_sel_hi:[1,0,1] neg_lo:[1,0,0] neg_hi:[1,0,0]
	ds_read_b128 v[188:191], v10 offset:55552
	ds_read_b128 v[196:199], v10 offset:56064
	ds_read_b128 v[192:195], v10 offset:55808
	v_fma_mix_f32 v12, v6, v88, v180 op_sel_hi:[0,1,0]
	v_fma_mix_f32 v12, v7, v88, v12 op_sel:[0,1,0] op_sel_hi:[0,1,0]
	v_fma_mix_f32 v12, v8, v89, v12 op_sel_hi:[0,1,0]
	v_fma_mix_f32 v12, v9, v89, v12 op_sel:[0,1,0] op_sel_hi:[0,1,0]
	v_fma_mix_f32 v123, v6, v38, v180 op_sel_hi:[0,1,0]
	v_fma_mix_f32 v123, v7, v38, v123 op_sel:[0,1,0] op_sel_hi:[0,1,0]
	v_add_f32_dpp v12, v12, v12 row_ror:1 row_mask:0xf bank_mask:0xf bound_ctrl:1
	v_fma_mix_f32 v123, v8, v39, v123 op_sel_hi:[0,1,0]
	v_fma_mix_f32 v123, v9, v39, v123 op_sel:[0,1,0] op_sel_hi:[0,1,0]
	v_add_f32_dpp v12, v12, v12 row_ror:2 row_mask:0xf bank_mask:0xf bound_ctrl:1
	v_pk_fma_f32 v[48:49], v[96:97], v[68:69], v[6:7] op_sel_hi:[1,0,1]
	v_pk_fma_f32 v[50:51], v[98:99], v[68:69], v[8:9] op_sel_hi:[1,0,1]
	v_add_f32_dpp v12, v12, v12 row_ror:4 row_mask:0xf bank_mask:0xf bound_ctrl:1
	v_add_f32_dpp v100, v53, v53 row_ror:8 row_mask:0xf bank_mask:0x3
	v_add_f32_dpp v101, v101, v101 row_ror:8 row_mask:0xf bank_mask:0xc
	v_add_f32_dpp v101, v54, v54 row_ror:8 row_mask:0xf bank_mask:0x3
	v_add_f32_dpp v12, v12, v12 row_ror:8 row_mask:0xf bank_mask:0xf bound_ctrl:1
	v_pk_fma_f32 v[6:7], v[92:93], v[12:13], v[48:49] op_sel_hi:[1,0,1] neg_lo:[1,0,0] neg_hi:[1,0,0]
	v_pk_fma_f32 v[8:9], v[94:95], v[12:13], v[50:51] op_sel_hi:[1,0,1] neg_lo:[1,0,0] neg_hi:[1,0,0]
	ds_read_b128 v[204:207], v10 offset:56576
	ds_read_b128 v[200:203], v10 offset:56320
	ds_read_b128 v[212:215], v10 offset:57088
	ds_read_b128 v[208:211], v10 offset:56832
	v_fma_mix_f32 v12, v6, v110, v180 op_sel_hi:[0,1,0]
	v_fma_mix_f32 v12, v7, v110, v12 op_sel:[0,1,0] op_sel_hi:[0,1,0]
	v_fma_mix_f32 v12, v8, v111, v12 op_sel_hi:[0,1,0]
	v_fma_mix_f32 v12, v9, v111, v12 op_sel:[0,1,0] op_sel_hi:[0,1,0]
	v_fma_mix_f32 v124, v6, v90, v180 op_sel_hi:[0,1,0]
	v_fma_mix_f32 v124, v7, v90, v124 op_sel:[0,1,0] op_sel_hi:[0,1,0]
	v_add_f32_dpp v12, v12, v12 row_ror:1 row_mask:0xf bank_mask:0xf bound_ctrl:1
	v_fma_mix_f32 v124, v8, v91, v124 op_sel_hi:[0,1,0]
	v_fma_mix_f32 v124, v9, v91, v124 op_sel:[0,1,0] op_sel_hi:[0,1,0]
	v_add_f32_dpp v12, v12, v12 row_ror:2 row_mask:0xf bank_mask:0xf bound_ctrl:1
	v_pk_fma_f32 v[48:49], v[118:119], v[68:69], v[6:7] op_sel:[0,1,0]
	v_pk_fma_f32 v[50:51], v[120:121], v[68:69], v[8:9] op_sel:[0,1,0]
	v_add_f32_dpp v12, v12, v12 row_ror:4 row_mask:0xf bank_mask:0xf bound_ctrl:1
	v_add_f32_dpp v102, v102, v102 row_ror:8 row_mask:0xf bank_mask:0xc
	v_add_f32_dpp v102, v55, v55 row_ror:8 row_mask:0xf bank_mask:0x3
	v_add_f32_dpp v103, v103, v103 row_ror:8 row_mask:0xf bank_mask:0xc
	v_add_f32_dpp v12, v12, v12 row_ror:8 row_mask:0xf bank_mask:0xf bound_ctrl:1
	v_pk_fma_f32 v[6:7], v[114:115], v[12:13], v[48:49] op_sel_hi:[1,0,1] neg_lo:[1,0,0] neg_hi:[1,0,0]
	v_pk_fma_f32 v[8:9], v[116:117], v[12:13], v[50:51] op_sel_hi:[1,0,1] neg_lo:[1,0,0] neg_hi:[1,0,0]
	v_pk_mul_f32 v[6:7], v[6:7], v[106:107]
	v_pk_mul_f32 v[8:9], v[8:9], v[108:109]
	s_waitcnt lgkmcnt(0)
	ds_read_b128 v[20:23], v10 offset:57600
	ds_read_b128 v[28:31], v10 offset:58112
	ds_read_b128 v[24:27], v10 offset:57856
	v_fma_mix_f32 v12, v6, v142, v180 op_sel_hi:[0,1,0]
	v_fma_mix_f32 v12, v7, v142, v12 op_sel:[0,1,0] op_sel_hi:[0,1,0]
	v_fma_mix_f32 v12, v8, v143, v12 op_sel_hi:[0,1,0]
	v_fma_mix_f32 v12, v9, v143, v12 op_sel:[0,1,0] op_sel_hi:[0,1,0]
	v_fma_mix_f32 v125, v6, v112, v180 op_sel_hi:[0,1,0]
	v_fma_mix_f32 v125, v7, v112, v125 op_sel:[0,1,0] op_sel_hi:[0,1,0]
	v_add_f32_dpp v12, v12, v12 row_ror:1 row_mask:0xf bank_mask:0xf bound_ctrl:1
	v_fma_mix_f32 v125, v8, v113, v125 op_sel_hi:[0,1,0]
	v_fma_mix_f32 v125, v9, v113, v125 op_sel:[0,1,0] op_sel_hi:[0,1,0]
	v_add_f32_dpp v12, v12, v12 row_ror:2 row_mask:0xf bank_mask:0xf bound_ctrl:1
	v_pk_fma_f32 v[48:49], v[150:151], v[70:71], v[6:7] op_sel_hi:[1,0,1]
	v_pk_fma_f32 v[50:51], v[152:153], v[70:71], v[8:9] op_sel_hi:[1,0,1]
	v_add_f32_dpp v12, v12, v12 row_ror:4 row_mask:0xf bank_mask:0xf bound_ctrl:1
	v_add_f32_dpp v103, v56, v56 row_ror:8 row_mask:0xf bank_mask:0x3
	v_add_f32_dpp v104, v104, v104 row_ror:8 row_mask:0xf bank_mask:0xc
	v_add_f32_dpp v104, v57, v57 row_ror:8 row_mask:0xf bank_mask:0x3
	v_add_f32_dpp v12, v12, v12 row_ror:8 row_mask:0xf bank_mask:0xf bound_ctrl:1
	v_pk_fma_f32 v[6:7], v[146:147], v[12:13], v[48:49] op_sel_hi:[1,0,1] neg_lo:[1,0,0] neg_hi:[1,0,0]
	v_pk_fma_f32 v[8:9], v[148:149], v[12:13], v[50:51] op_sel_hi:[1,0,1] neg_lo:[1,0,0] neg_hi:[1,0,0]
	ds_read_b128 v[36:39], v10 offset:58624
	ds_read_b128 v[44:47], v10 offset:59136
	ds_read_b128 v[40:43], v10 offset:58880
	ds_read_b128 v[66:69], v11 offset:3584
	v_fma_mix_f32 v12, v6, v158, v180 op_sel_hi:[0,1,0]
	v_fma_mix_f32 v12, v7, v158, v12 op_sel:[0,1,0] op_sel_hi:[0,1,0]
	v_fma_mix_f32 v12, v8, v159, v12 op_sel_hi:[0,1,0]
	v_fma_mix_f32 v12, v9, v159, v12 op_sel:[0,1,0] op_sel_hi:[0,1,0]
	v_fma_mix_f32 v126, v6, v144, v180 op_sel_hi:[0,1,0]
	v_fma_mix_f32 v126, v7, v144, v126 op_sel:[0,1,0] op_sel_hi:[0,1,0]
	v_add_f32_dpp v12, v12, v12 row_ror:1 row_mask:0xf bank_mask:0xf bound_ctrl:1
	v_fma_mix_f32 v126, v8, v145, v126 op_sel_hi:[0,1,0]
	v_fma_mix_f32 v126, v9, v145, v126 op_sel:[0,1,0] op_sel_hi:[0,1,0]
	v_add_f32_dpp v12, v12, v12 row_ror:2 row_mask:0xf bank_mask:0xf bound_ctrl:1
	v_pk_fma_f32 v[48:49], v[166:167], v[70:71], v[6:7] op_sel:[0,1,0]
	v_pk_fma_f32 v[50:51], v[168:169], v[70:71], v[8:9] op_sel:[0,1,0]
	v_add_f32_dpp v12, v12, v12 row_ror:4 row_mask:0xf bank_mask:0xf bound_ctrl:1
	v_add_f32_dpp v105, v105, v105 row_ror:8 row_mask:0xf bank_mask:0xc
	v_add_f32_dpp v105, v81, v81 row_ror:8 row_mask:0xf bank_mask:0x3
	v_add_f32_dpp v12, v12, v12 row_ror:8 row_mask:0xf bank_mask:0xf bound_ctrl:1
	v_pk_fma_f32 v[6:7], v[162:163], v[12:13], v[48:49] op_sel_hi:[1,0,1] neg_lo:[1,0,0] neg_hi:[1,0,0]
	v_pk_fma_f32 v[8:9], v[164:165], v[12:13], v[50:51] op_sel_hi:[1,0,1] neg_lo:[1,0,0] neg_hi:[1,0,0]
	ds_read_b128 v[88:91], v10 offset:59648
	ds_read_b128 v[96:99], v10 offset:60160
	ds_read_b128 v[92:95], v10 offset:59904
	v_fma_mix_f32 v12, v6, v188, v180 op_sel_hi:[0,1,0]
	v_fma_mix_f32 v12, v7, v188, v12 op_sel:[0,1,0] op_sel_hi:[0,1,0]
	v_fma_mix_f32 v12, v8, v189, v12 op_sel_hi:[0,1,0]
	v_fma_mix_f32 v12, v9, v189, v12 op_sel:[0,1,0] op_sel_hi:[0,1,0]
	v_fma_mix_f32 v127, v6, v160, v180 op_sel_hi:[0,1,0]
	v_fma_mix_f32 v127, v7, v160, v127 op_sel:[0,1,0] op_sel_hi:[0,1,0]
	v_add_f32_dpp v12, v12, v12 row_ror:1 row_mask:0xf bank_mask:0xf bound_ctrl:1
	v_fma_mix_f32 v127, v8, v161, v127 op_sel_hi:[0,1,0]
	v_fma_mix_f32 v127, v9, v161, v127 op_sel:[0,1,0] op_sel_hi:[0,1,0]
	v_add_f32_dpp v12, v12, v12 row_ror:2 row_mask:0xf bank_mask:0xf bound_ctrl:1
	v_pk_fma_f32 v[48:49], v[196:197], v[72:73], v[6:7] op_sel_hi:[1,0,1]
	v_pk_fma_f32 v[50:51], v[198:199], v[72:73], v[8:9] op_sel_hi:[1,0,1]
	v_add_f32_dpp v12, v12, v12 row_ror:4 row_mask:0xf bank_mask:0xf bound_ctrl:1
	v_add_f32_dpp v61, v61, v61 row_ror:8 row_mask:0xf bank_mask:0xc
	v_add_f32_dpp v61, v82, v82 row_ror:8 row_mask:0xf bank_mask:0x3
	v_add_f32_dpp v12, v12, v12 row_ror:8 row_mask:0xf bank_mask:0xf bound_ctrl:1
	v_pk_fma_f32 v[6:7], v[192:193], v[12:13], v[48:49] op_sel_hi:[1,0,1] neg_lo:[1,0,0] neg_hi:[1,0,0]
	v_pk_fma_f32 v[8:9], v[194:195], v[12:13], v[50:51] op_sel_hi:[1,0,1] neg_lo:[1,0,0] neg_hi:[1,0,0]
	ds_read_b128 v[110:113], v10 offset:60672
	ds_read_b128 v[106:109], v10 offset:60416
	ds_read_b128 v[118:121], v10 offset:61184
	ds_read_b128 v[114:117], v10 offset:60928
	v_fma_mix_f32 v12, v6, v204, v180 op_sel_hi:[0,1,0]
	v_fma_mix_f32 v12, v7, v204, v12 op_sel:[0,1,0] op_sel_hi:[0,1,0]
	v_fma_mix_f32 v12, v8, v205, v12 op_sel_hi:[0,1,0]
	v_fma_mix_f32 v12, v9, v205, v12 op_sel:[0,1,0] op_sel_hi:[0,1,0]
	v_fma_mix_f32 v128, v6, v190, v180 op_sel_hi:[0,1,0]
	v_fma_mix_f32 v128, v7, v190, v128 op_sel:[0,1,0] op_sel_hi:[0,1,0]
	v_add_f32_dpp v12, v12, v12 row_ror:1 row_mask:0xf bank_mask:0xf bound_ctrl:1
	v_fma_mix_f32 v128, v8, v191, v128 op_sel_hi:[0,1,0]
	v_fma_mix_f32 v128, v9, v191, v128 op_sel:[0,1,0] op_sel_hi:[0,1,0]
	v_add_f32_dpp v12, v12, v12 row_ror:2 row_mask:0xf bank_mask:0xf bound_ctrl:1
	v_pk_fma_f32 v[48:49], v[212:213], v[72:73], v[6:7] op_sel:[0,1,0]
	v_pk_fma_f32 v[50:51], v[214:215], v[72:73], v[8:9] op_sel:[0,1,0]
	v_add_f32_dpp v12, v12, v12 row_ror:4 row_mask:0xf bank_mask:0xf bound_ctrl:1
	v_add_f32_dpp v103, v103, v103 row_ror:4 row_mask:0xf bank_mask:0xa
	v_add_f32_dpp v103, v83, v83 row_ror:12 row_mask:0xf bank_mask:0x5
	v_add_f32_dpp v104, v104, v104 row_ror:4 row_mask:0xf bank_mask:0xa
	v_add_f32_dpp v12, v12, v12 row_ror:8 row_mask:0xf bank_mask:0xf bound_ctrl:1
	v_pk_fma_f32 v[6:7], v[208:209], v[12:13], v[48:49] op_sel_hi:[1,0,1] neg_lo:[1,0,0] neg_hi:[1,0,0]
	v_pk_fma_f32 v[8:9], v[210:211], v[12:13], v[50:51] op_sel_hi:[1,0,1] neg_lo:[1,0,0] neg_hi:[1,0,0]
	v_pk_mul_f32 v[6:7], v[6:7], v[200:201]
	v_pk_mul_f32 v[8:9], v[8:9], v[202:203]
	s_waitcnt lgkmcnt(0)
	ds_read_b128 v[142:145], v10 offset:61696
	ds_read_b128 v[150:153], v10 offset:62208
	ds_read_b128 v[146:149], v10 offset:61952
	v_fma_mix_f32 v12, v6, v20, v180 op_sel_hi:[0,1,0]
	v_fma_mix_f32 v12, v7, v20, v12 op_sel:[0,1,0] op_sel_hi:[0,1,0]
	v_fma_mix_f32 v12, v8, v21, v12 op_sel_hi:[0,1,0]
	v_fma_mix_f32 v12, v9, v21, v12 op_sel:[0,1,0] op_sel_hi:[0,1,0]
	v_fma_mix_f32 v129, v6, v206, v180 op_sel_hi:[0,1,0]
	v_fma_mix_f32 v129, v7, v206, v129 op_sel:[0,1,0] op_sel_hi:[0,1,0]
	v_add_f32_dpp v12, v12, v12 row_ror:1 row_mask:0xf bank_mask:0xf bound_ctrl:1
	v_fma_mix_f32 v129, v8, v207, v129 op_sel_hi:[0,1,0]
	v_fma_mix_f32 v129, v9, v207, v129 op_sel:[0,1,0] op_sel_hi:[0,1,0]
	v_add_f32_dpp v12, v12, v12 row_ror:2 row_mask:0xf bank_mask:0xf bound_ctrl:1
	v_pk_fma_f32 v[48:49], v[28:29], v[66:67], v[6:7] op_sel_hi:[1,0,1]
	v_pk_fma_f32 v[50:51], v[30:31], v[66:67], v[8:9] op_sel_hi:[1,0,1]
	v_add_f32_dpp v12, v12, v12 row_ror:4 row_mask:0xf bank_mask:0xf bound_ctrl:1
	v_add_f32_dpp v104, v100, v100 row_ror:12 row_mask:0xf bank_mask:0x5
	v_add_f32_dpp v105, v105, v105 row_ror:4 row_mask:0xf bank_mask:0xa
	v_add_f32_dpp v105, v101, v101 row_ror:12 row_mask:0xf bank_mask:0x5
	v_add_f32_dpp v12, v12, v12 row_ror:8 row_mask:0xf bank_mask:0xf bound_ctrl:1
	v_pk_fma_f32 v[6:7], v[24:25], v[12:13], v[48:49] op_sel_hi:[1,0,1] neg_lo:[1,0,0] neg_hi:[1,0,0]
	v_pk_fma_f32 v[8:9], v[26:27], v[12:13], v[50:51] op_sel_hi:[1,0,1] neg_lo:[1,0,0] neg_hi:[1,0,0]
	ds_read_b128 v[158:161], v10 offset:62720
	ds_read_b128 v[166:169], v10 offset:63232
	ds_read_b128 v[162:165], v10 offset:62976
	ds_read_b128 v[70:73], v11 offset:3840
	v_fma_mix_f32 v12, v6, v36, v180 op_sel_hi:[0,1,0]
	v_fma_mix_f32 v12, v7, v36, v12 op_sel:[0,1,0] op_sel_hi:[0,1,0]
	v_fma_mix_f32 v12, v8, v37, v12 op_sel_hi:[0,1,0]
	v_fma_mix_f32 v12, v9, v37, v12 op_sel:[0,1,0] op_sel_hi:[0,1,0]
	v_fma_mix_f32 v130, v6, v22, v180 op_sel_hi:[0,1,0]
	v_fma_mix_f32 v130, v7, v22, v130 op_sel:[0,1,0] op_sel_hi:[0,1,0]
	v_add_f32_dpp v12, v12, v12 row_ror:1 row_mask:0xf bank_mask:0xf bound_ctrl:1
	v_fma_mix_f32 v130, v8, v23, v130 op_sel_hi:[0,1,0]
	v_fma_mix_f32 v130, v9, v23, v130 op_sel:[0,1,0] op_sel_hi:[0,1,0]
	v_add_f32_dpp v12, v12, v12 row_ror:2 row_mask:0xf bank_mask:0xf bound_ctrl:1
	v_pk_fma_f32 v[48:49], v[44:45], v[66:67], v[6:7] op_sel:[0,1,0]
	v_pk_fma_f32 v[50:51], v[46:47], v[66:67], v[8:9] op_sel:[0,1,0]
	v_add_f32_dpp v12, v12, v12 row_ror:4 row_mask:0xf bank_mask:0xf bound_ctrl:1
	v_add_f32_dpp v61, v61, v61 row_ror:4 row_mask:0xf bank_mask:0xa
	v_add_f32_dpp v61, v102, v102 row_ror:12 row_mask:0xf bank_mask:0x5
	v_add_f32_dpp v12, v12, v12 row_ror:8 row_mask:0xf bank_mask:0xf bound_ctrl:1
	v_pk_fma_f32 v[6:7], v[40:41], v[12:13], v[48:49] op_sel_hi:[1,0,1] neg_lo:[1,0,0] neg_hi:[1,0,0]
	v_pk_fma_f32 v[8:9], v[42:43], v[12:13], v[50:51] op_sel_hi:[1,0,1] neg_lo:[1,0,0] neg_hi:[1,0,0]
	ds_read_b128 v[188:191], v10 offset:63744
	ds_read_b128 v[196:199], v10 offset:64256
	ds_read_b128 v[192:195], v10 offset:64000
	v_fma_mix_f32 v12, v6, v88, v180 op_sel_hi:[0,1,0]
	v_fma_mix_f32 v12, v7, v88, v12 op_sel:[0,1,0] op_sel_hi:[0,1,0]
	v_fma_mix_f32 v12, v8, v89, v12 op_sel_hi:[0,1,0]
	v_fma_mix_f32 v12, v9, v89, v12 op_sel:[0,1,0] op_sel_hi:[0,1,0]
	v_fma_mix_f32 v131, v6, v38, v180 op_sel_hi:[0,1,0]
	v_fma_mix_f32 v131, v7, v38, v131 op_sel:[0,1,0] op_sel_hi:[0,1,0]
	v_add_f32_dpp v12, v12, v12 row_ror:1 row_mask:0xf bank_mask:0xf bound_ctrl:1
	v_fma_mix_f32 v131, v8, v39, v131 op_sel_hi:[0,1,0]
	v_fma_mix_f32 v131, v9, v39, v131 op_sel:[0,1,0] op_sel_hi:[0,1,0]
	v_add_f32_dpp v12, v12, v12 row_ror:2 row_mask:0xf bank_mask:0xf bound_ctrl:1
	v_pk_fma_f32 v[48:49], v[96:97], v[68:69], v[6:7] op_sel_hi:[1,0,1]
	v_pk_fma_f32 v[50:51], v[98:99], v[68:69], v[8:9] op_sel_hi:[1,0,1]
	v_add_f32_dpp v12, v12, v12 row_ror:4 row_mask:0xf bank_mask:0xf bound_ctrl:1
	v_cndmask_b32_e64 v62, v105, v103, s[38:39]
	v_cndmask_b32_e64 v63, v103, v105, s[38:39]
	v_add_f32_dpp v12, v12, v12 row_ror:8 row_mask:0xf bank_mask:0xf bound_ctrl:1
	v_pk_fma_f32 v[6:7], v[92:93], v[12:13], v[48:49] op_sel_hi:[1,0,1] neg_lo:[1,0,0] neg_hi:[1,0,0]
	v_pk_fma_f32 v[8:9], v[94:95], v[12:13], v[50:51] op_sel_hi:[1,0,1] neg_lo:[1,0,0] neg_hi:[1,0,0]
	ds_read_b128 v[204:207], v10 offset:64768
	ds_read_b128 v[200:203], v10 offset:64512
	ds_read_b128 v[212:215], v10 offset:65280
	ds_read_b128 v[208:211], v10 offset:65024
	v_fma_mix_f32 v12, v6, v110, v180 op_sel_hi:[0,1,0]
	v_fma_mix_f32 v12, v7, v110, v12 op_sel:[0,1,0] op_sel_hi:[0,1,0]
	v_fma_mix_f32 v12, v8, v111, v12 op_sel_hi:[0,1,0]
	v_fma_mix_f32 v12, v9, v111, v12 op_sel:[0,1,0] op_sel_hi:[0,1,0]
	v_fma_mix_f32 v132, v6, v90, v180 op_sel_hi:[0,1,0]
	v_fma_mix_f32 v132, v7, v90, v132 op_sel:[0,1,0] op_sel_hi:[0,1,0]
	v_add_f32_dpp v12, v12, v12 row_ror:1 row_mask:0xf bank_mask:0xf bound_ctrl:1
	v_fma_mix_f32 v132, v8, v91, v132 op_sel_hi:[0,1,0]
	v_fma_mix_f32 v132, v9, v91, v132 op_sel:[0,1,0] op_sel_hi:[0,1,0]
	v_add_f32_dpp v12, v12, v12 row_ror:2 row_mask:0xf bank_mask:0xf bound_ctrl:1
	v_pk_fma_f32 v[48:49], v[118:119], v[68:69], v[6:7] op_sel:[0,1,0]
	v_pk_fma_f32 v[50:51], v[120:121], v[68:69], v[8:9] op_sel:[0,1,0]
	v_add_f32_dpp v12, v12, v12 row_ror:4 row_mask:0xf bank_mask:0xf bound_ctrl:1
	v_cndmask_b32_e64 v64, v61, v104, s[38:39]
	v_cndmask_b32_e64 v65, v104, v61, s[38:39]
	v_add_f32_dpp v12, v12, v12 row_ror:8 row_mask:0xf bank_mask:0xf bound_ctrl:1
	v_pk_fma_f32 v[6:7], v[114:115], v[12:13], v[48:49] op_sel_hi:[1,0,1] neg_lo:[1,0,0] neg_hi:[1,0,0]
	v_pk_fma_f32 v[8:9], v[116:117], v[12:13], v[50:51] op_sel_hi:[1,0,1] neg_lo:[1,0,0] neg_hi:[1,0,0]
	v_pk_mul_f32 v[6:7], v[6:7], v[106:107]
	v_pk_mul_f32 v[8:9], v[8:9], v[108:109]
	s_waitcnt lgkmcnt(0)
	v_fma_mix_f32 v12, v6, v142, v180 op_sel_hi:[0,1,0]
	v_fma_mix_f32 v12, v7, v142, v12 op_sel:[0,1,0] op_sel_hi:[0,1,0]
	v_fma_mix_f32 v12, v8, v143, v12 op_sel_hi:[0,1,0]
	v_fma_mix_f32 v12, v9, v143, v12 op_sel:[0,1,0] op_sel_hi:[0,1,0]
	v_fma_mix_f32 v133, v6, v112, v180 op_sel_hi:[0,1,0]
	v_fma_mix_f32 v133, v7, v112, v133 op_sel:[0,1,0] op_sel_hi:[0,1,0]
	v_add_f32_dpp v12, v12, v12 row_ror:1 row_mask:0xf bank_mask:0xf bound_ctrl:1
	v_fma_mix_f32 v133, v8, v113, v133 op_sel_hi:[0,1,0]
	v_fma_mix_f32 v133, v9, v113, v133 op_sel:[0,1,0] op_sel_hi:[0,1,0]
	v_add_f32_dpp v12, v12, v12 row_ror:2 row_mask:0xf bank_mask:0xf bound_ctrl:1
	v_pk_fma_f32 v[48:49], v[150:151], v[70:71], v[6:7] op_sel_hi:[1,0,1]
	v_pk_fma_f32 v[50:51], v[152:153], v[70:71], v[8:9] op_sel_hi:[1,0,1]
	v_add_f32_dpp v12, v12, v12 row_ror:4 row_mask:0xf bank_mask:0xf bound_ctrl:1
	v_add_f32_dpp v62, v63, v62 quad_perm:[2,3,0,1] row_mask:0xf bank_mask:0xf bound_ctrl:1
	v_add_f32_dpp v63, v65, v64 quad_perm:[2,3,0,1] row_mask:0xf bank_mask:0xf bound_ctrl:1
	v_add_f32_dpp v12, v12, v12 row_ror:8 row_mask:0xf bank_mask:0xf bound_ctrl:1
	v_pk_fma_f32 v[6:7], v[146:147], v[12:13], v[48:49] op_sel_hi:[1,0,1] neg_lo:[1,0,0] neg_hi:[1,0,0]
	v_pk_fma_f32 v[8:9], v[148:149], v[12:13], v[50:51] op_sel_hi:[1,0,1] neg_lo:[1,0,0] neg_hi:[1,0,0]
	v_fma_mix_f32 v12, v6, v158, v180 op_sel_hi:[0,1,0]
	v_fma_mix_f32 v12, v7, v158, v12 op_sel:[0,1,0] op_sel_hi:[0,1,0]
	v_fma_mix_f32 v12, v8, v159, v12 op_sel_hi:[0,1,0]
	v_fma_mix_f32 v12, v9, v159, v12 op_sel:[0,1,0] op_sel_hi:[0,1,0]
	v_fma_mix_f32 v134, v6, v144, v180 op_sel_hi:[0,1,0]
	v_fma_mix_f32 v134, v7, v144, v134 op_sel:[0,1,0] op_sel_hi:[0,1,0]
	v_add_f32_dpp v12, v12, v12 row_ror:1 row_mask:0xf bank_mask:0xf bound_ctrl:1
	v_fma_mix_f32 v134, v8, v145, v134 op_sel_hi:[0,1,0]
	v_fma_mix_f32 v134, v9, v145, v134 op_sel:[0,1,0] op_sel_hi:[0,1,0]
	v_add_f32_dpp v12, v12, v12 row_ror:2 row_mask:0xf bank_mask:0xf bound_ctrl:1
	v_pk_fma_f32 v[48:49], v[166:167], v[70:71], v[6:7] op_sel:[0,1,0]
	v_pk_fma_f32 v[50:51], v[168:169], v[70:71], v[8:9] op_sel:[0,1,0]
	v_add_f32_dpp v12, v12, v12 row_ror:4 row_mask:0xf bank_mask:0xf bound_ctrl:1
	v_cndmask_b32_e64 v65, v63, v62, s[40:41]
	v_cndmask_b32_e64 v62, v62, v63, s[40:41]
	v_add_f32_dpp v12, v12, v12 row_ror:8 row_mask:0xf bank_mask:0xf bound_ctrl:1
	v_pk_fma_f32 v[6:7], v[162:163], v[12:13], v[48:49] op_sel_hi:[1,0,1] neg_lo:[1,0,0] neg_hi:[1,0,0]
	v_pk_fma_f32 v[8:9], v[164:165], v[12:13], v[50:51] op_sel_hi:[1,0,1] neg_lo:[1,0,0] neg_hi:[1,0,0]
	v_fma_mix_f32 v12, v6, v188, v180 op_sel_hi:[0,1,0]
	v_fma_mix_f32 v12, v7, v188, v12 op_sel:[0,1,0] op_sel_hi:[0,1,0]
	v_fma_mix_f32 v12, v8, v189, v12 op_sel_hi:[0,1,0]
	v_fma_mix_f32 v12, v9, v189, v12 op_sel:[0,1,0] op_sel_hi:[0,1,0]
	v_fma_mix_f32 v135, v6, v160, v180 op_sel_hi:[0,1,0]
	v_fma_mix_f32 v135, v7, v160, v135 op_sel:[0,1,0] op_sel_hi:[0,1,0]
	v_add_f32_dpp v12, v12, v12 row_ror:1 row_mask:0xf bank_mask:0xf bound_ctrl:1
	v_fma_mix_f32 v135, v8, v161, v135 op_sel_hi:[0,1,0]
	v_fma_mix_f32 v135, v9, v161, v135 op_sel:[0,1,0] op_sel_hi:[0,1,0]
	v_add_f32_dpp v12, v12, v12 row_ror:2 row_mask:0xf bank_mask:0xf bound_ctrl:1
	v_pk_fma_f32 v[48:49], v[196:197], v[72:73], v[6:7] op_sel_hi:[1,0,1]
	v_pk_fma_f32 v[50:51], v[198:199], v[72:73], v[8:9] op_sel_hi:[1,0,1]
	v_add_f32_dpp v12, v12, v12 row_ror:4 row_mask:0xf bank_mask:0xf bound_ctrl:1
	v_add_f32_dpp v62, v62, v65 quad_perm:[1,0,3,2] row_mask:0xf bank_mask:0xf bound_ctrl:1
	v_cvt_pk_bf16_f32 v62, v62, v62
	v_add_f32_dpp v12, v12, v12 row_ror:8 row_mask:0xf bank_mask:0xf bound_ctrl:1
	v_pk_fma_f32 v[6:7], v[192:193], v[12:13], v[48:49] op_sel_hi:[1,0,1] neg_lo:[1,0,0] neg_hi:[1,0,0]
	v_pk_fma_f32 v[8:9], v[194:195], v[12:13], v[50:51] op_sel_hi:[1,0,1] neg_lo:[1,0,0] neg_hi:[1,0,0]
	s_waitcnt lgkmcnt(0)
	s_barrier
	v_xor_b32_e32 v10, 0x10000, v10
	v_xor_b32_e32 v11, 0x1000, v11
	ds_read_b128 v[66:69], v11 offset:0
	ds_read_b128 v[20:23], v10 offset:256
	ds_read_b128 v[28:31], v10 offset:768
	ds_read_b128 v[24:27], v10 offset:512
	ds_read_b128 v[36:39], v10 offset:1280
	ds_read_b128 v[44:47], v10 offset:1792
	ds_read_b128 v[40:43], v10 offset:1536
	ds_read_b128 v[88:91], v10 offset:2304
	ds_read_b128 v[96:99], v10 offset:2816
	ds_read_b128 v[92:95], v10 offset:2560
	ds_read_b128 v[110:113], v10 offset:3328
	ds_read_b128 v[106:109], v10 offset:3072
	ds_read_b128 v[118:121], v10 offset:3840
	ds_read_b128 v[114:117], v10 offset:3584
	v_fma_mix_f32 v12, v6, v204, v180 op_sel_hi:[0,1,0]
	v_fma_mix_f32 v12, v7, v204, v12 op_sel:[0,1,0] op_sel_hi:[0,1,0]
	v_fma_mix_f32 v12, v8, v205, v12 op_sel_hi:[0,1,0]
	v_fma_mix_f32 v12, v9, v205, v12 op_sel:[0,1,0] op_sel_hi:[0,1,0]
	v_fma_mix_f32 v136, v6, v190, v180 op_sel_hi:[0,1,0]
	v_fma_mix_f32 v136, v7, v190, v136 op_sel:[0,1,0] op_sel_hi:[0,1,0]
	v_add_f32_dpp v12, v12, v12 row_ror:1 row_mask:0xf bank_mask:0xf bound_ctrl:1
	v_fma_mix_f32 v136, v8, v191, v136 op_sel_hi:[0,1,0]
	v_fma_mix_f32 v136, v9, v191, v136 op_sel:[0,1,0] op_sel_hi:[0,1,0]
	v_add_f32_dpp v12, v12, v12 row_ror:2 row_mask:0xf bank_mask:0xf bound_ctrl:1
	v_pk_fma_f32 v[48:49], v[212:213], v[72:73], v[6:7] op_sel:[0,1,0]
	v_pk_fma_f32 v[50:51], v[214:215], v[72:73], v[8:9] op_sel:[0,1,0]
	v_add_f32_dpp v12, v12, v12 row_ror:4 row_mask:0xf bank_mask:0xf bound_ctrl:1
	global_store_short v[2:3], v62, off
	v_lshl_add_u64 v[2:3], v[2:3], 0, s[84:85]
	v_add_f32_dpp v12, v12, v12 row_ror:8 row_mask:0xf bank_mask:0xf bound_ctrl:1
	v_pk_fma_f32 v[6:7], v[208:209], v[12:13], v[48:49] op_sel_hi:[1,0,1] neg_lo:[1,0,0] neg_hi:[1,0,0]
	v_pk_fma_f32 v[8:9], v[210:211], v[12:13], v[50:51] op_sel_hi:[1,0,1] neg_lo:[1,0,0] neg_hi:[1,0,0]
	v_pk_mul_f32 v[6:7], v[6:7], v[200:201]
	v_pk_mul_f32 v[8:9], v[8:9], v[202:203]
	v_fma_mix_f32 v137, v6, v206, v180 op_sel_hi:[0,1,0]
	v_fma_mix_f32 v137, v7, v206, v137 op_sel:[0,1,0] op_sel_hi:[0,1,0]
	v_fma_mix_f32 v137, v8, v207, v137 op_sel_hi:[0,1,0]
	v_fma_mix_f32 v137, v9, v207, v137 op_sel:[0,1,0] op_sel_hi:[0,1,0]
	v_add_f32_dpp v130, v130, v130 row_ror:8 row_mask:0xf bank_mask:0xc
	v_add_f32_dpp v130, v122, v122 row_ror:8 row_mask:0xf bank_mask:0x3
	v_add_f32_dpp v131, v131, v131 row_ror:8 row_mask:0xf bank_mask:0xc
	v_add_f32_dpp v131, v123, v123 row_ror:8 row_mask:0xf bank_mask:0x3
	v_add_f32_dpp v132, v132, v132 row_ror:8 row_mask:0xf bank_mask:0xc
	v_add_f32_dpp v132, v124, v124 row_ror:8 row_mask:0xf bank_mask:0x3
	v_add_f32_dpp v133, v133, v133 row_ror:8 row_mask:0xf bank_mask:0xc
	v_add_f32_dpp v133, v125, v125 row_ror:8 row_mask:0xf bank_mask:0x3
	v_add_f32_dpp v134, v134, v134 row_ror:8 row_mask:0xf bank_mask:0xc
	v_add_f32_dpp v134, v126, v126 row_ror:8 row_mask:0xf bank_mask:0x3
	v_add_f32_dpp v135, v135, v135 row_ror:8 row_mask:0xf bank_mask:0xc
	v_add_f32_dpp v135, v127, v127 row_ror:8 row_mask:0xf bank_mask:0x3
	v_add_f32_dpp v136, v136, v136 row_ror:8 row_mask:0xf bank_mask:0xc
	v_add_f32_dpp v136, v128, v128 row_ror:8 row_mask:0xf bank_mask:0x3
	v_add_f32_dpp v137, v137, v137 row_ror:8 row_mask:0xf bank_mask:0xc
	v_add_f32_dpp v137, v129, v129 row_ror:8 row_mask:0xf bank_mask:0x3
	v_add_f32_dpp v134, v134, v134 row_ror:4 row_mask:0xf bank_mask:0xa
	v_add_f32_dpp v134, v130, v130 row_ror:12 row_mask:0xf bank_mask:0x5
	v_add_f32_dpp v135, v135, v135 row_ror:4 row_mask:0xf bank_mask:0xa
	v_add_f32_dpp v135, v131, v131 row_ror:12 row_mask:0xf bank_mask:0x5
	v_add_f32_dpp v136, v136, v136 row_ror:4 row_mask:0xf bank_mask:0xa
	v_add_f32_dpp v136, v132, v132 row_ror:12 row_mask:0xf bank_mask:0x5
	v_add_f32_dpp v137, v137, v137 row_ror:4 row_mask:0xf bank_mask:0xa
	v_add_f32_dpp v137, v133, v133 row_ror:12 row_mask:0xf bank_mask:0x5
	v_cndmask_b32_e64 v62, v136, v134, s[38:39]
	v_cndmask_b32_e64 v63, v134, v136, s[38:39]
	v_cndmask_b32_e64 v64, v137, v135, s[38:39]
	v_cndmask_b32_e64 v65, v135, v137, s[38:39]
	v_add_f32_dpp v62, v63, v62 quad_perm:[2,3,0,1] row_mask:0xf bank_mask:0xf bound_ctrl:1
	s_nop 0
	v_add_f32_dpp v63, v65, v64 quad_perm:[2,3,0,1] row_mask:0xf bank_mask:0xf bound_ctrl:1
	v_cndmask_b32_e64 v65, v63, v62, s[40:41]
	v_cndmask_b32_e64 v62, v62, v63, s[40:41]
	s_nop 1
	v_add_f32_dpp v62, v62, v65 quad_perm:[1,0,3,2] row_mask:0xf bank_mask:0xf bound_ctrl:1
	v_cvt_pk_bf16_f32 v62, v62, v62
	global_store_short v[2:3], v62, off
	s_cmp_lg_u32 s28, 0x800000
	s_cbranch_scc1 .Lscan_cons_chunk
	s_branch .LBB0_53
